# GEMM k-loops (P1, P3, P6, P7): guard-free copy of the loop body when every row of the tile is valid (no per-half s_and_saveexec / s_cbranch_execz, no mid-loop taken branch)
# speedup vs baseline: 1.0133x; 1.0005x over previous
; __device__ __forceinline__ int vtid() { int t = threadIdx.x; asm volatile("" : "+v"(t)); return t; }
; template <int K, class FA, class FB, class Epi>
; __device__ __forceinline__ void gemm_tile(char* smem, int nvalid_rows, FA rowA, FB rowB, Epi epi) {
;   const int tid = vtid(), lane = tid & 63, wid = tid >> 6, wr = wid >> 1, wc = wid & 1, fr = lane & 15, fq = lane >> 4;
;   const int seg = tid & 3, r0 = tid >> 2;
;   int msub = (nvalid_rows - wr * 128 + 15) >> 4;
;   msub = msub < 0 ? 0 : (msub > 8 ? 8 : msub);
;   const u16* pa0 = rowA(r0) + seg * 8;
;   const u16* pa1 = rowA(r0 + 64) + seg * 8;
;   const u16* pa2 = rowA(r0 + 128) + seg * 8;
;   const u16* pa3 = rowA(r0 + 192) + seg * 8;
;   const u16* pb0 = rowB(r0) + seg * 8;
;   const u16* pb1 = rowB(r0 + 64) + seg * 8;
;   f32x4 acc[8][4];
; #pragma unroll
;   for (int m = 0; m < 8; ++m)
; #pragma unroll
;     for (int n = 0; n < 4; ++n) acc[m][n] = (f32x4){0.f, 0.f, 0.f, 0.f};
;   uint4 ra0, ra1, ra2, ra3, rb0, rb1;
;   ra0 = *(const uint4*)pa0; ra1 = *(const uint4*)pa1; ra2 = *(const uint4*)pa2; ra3 = *(const uint4*)pa3;
;   rb0 = *(const uint4*)pb0; rb1 = *(const uint4*)pb1;
;   constexpr int NK = K / 32;
;   const int wsw = (seg ^ ((r0 >> 2) & 3)) * 8;
;   const int wofsA = r0 * 32 + wsw, wofsB = 256 * 32 + r0 * 32 + wsw;
;   __syncthreads();
;   {
;     u16* B0 = (u16*)smem;
;     *(uint4*)&B0[wofsA] = ra0; *(uint4*)&B0[wofsA + 64 * 32] = ra1;
;     *(uint4*)&B0[wofsA + 128 * 32] = ra2; *(uint4*)&B0[wofsA + 192 * 32] = ra3;
;     *(uint4*)&B0[wofsB] = rb0; *(uint4*)&B0[wofsB + 64 * 32] = rb1;
;   }
;   ra0 = *(const uint4*)(pa0 + 32); ra1 = *(const uint4*)(pa1 + 32); ra2 = *(const uint4*)(pa2 + 32); ra3 = *(const uint4*)(pa3 + 32);
;   rb0 = *(const uint4*)(pb0 + 32); rb1 = *(const uint4*)(pb1 + 32);
;   __syncthreads();
;   const int rsw = (fq ^ ((fr >> 2) & 3)) * 8;
;   const int rdA = (wr * 128 + fr) * 32 + rsw, rdB = 256 * 32 + (wc * 64 + fr) * 32 + rsw;
; __device__ __forceinline__ void inproj_tile(const Params& p, char* smem, int l, int mt, int nt) {
;     ...
;   auto rowA = [&](int r) { return HL + (size_t)(mt * 256 + r) * 1024; };
;   auto rowB = [&](int r) { return W + (size_t)(nt * 128 + r) * 1024; };
.LBB0_295:
	s_mul_hi_i32 s0, s2, 0x66666667
	s_lshr_b32 s1, s0, 31
	s_ashr_i32 s0, s0, 3
	s_add_i32 s6, s0, s1
	s_mul_i32 s0, s6, 20
	s_sub_i32 s13, s2, s0
	s_mov_b64 s[8:9], s[58:59]
	s_mov_b32 s12, s24
	s_add_u32 s0, s8, 0x1b2d6100
	s_addc_u32 s1, s9, 0
	s_mul_i32 s4, s12, 0x500000
	s_mul_hi_i32 s5, s12, 0x500000
	s_add_u32 s4, s8, s4
	v_mov_b32_e32 v169, v172
	s_addc_u32 s5, s9, s5
	s_lshl_b32 s6, s6, 8
	s_waitcnt vmcnt(0)
	v_ashrrev_i32_e32 v50, 2, v169
	v_add_u32_e32 v2, s6, v50
	v_ashrrev_i32_e32 v3, 31, v2
	v_add_u32_e32 v0, 64, v50
	s_lshl_b32 s7, s13, 7
	v_lshlrev_b64 v[26:27], 11, v[2:3]
	v_add_u32_e32 v4, s6, v0
	v_add_u32_e32 v6, 0x80, v2
	v_add_u32_e32 v2, 0xc0, v2
	v_add_u32_e32 v8, s7, v50
	v_add_u32_e32 v10, s7, v0
	v_ashrrev_i32_e32 v5, 31, v4
	v_ashrrev_i32_e32 v7, 31, v6
	v_ashrrev_i32_e32 v3, 31, v2
	v_ashrrev_i32_e32 v9, 31, v8
	v_ashrrev_i32_e32 v11, 31, v10
	v_lshlrev_b32_e32 v0, 4, v169
	v_lshlrev_b64 v[28:29], 11, v[4:5]
	v_lshlrev_b64 v[30:31], 11, v[6:7]
	v_lshlrev_b64 v[32:33], 11, v[2:3]
	v_lshlrev_b64 v[34:35], 11, v[8:9]
	v_lshlrev_b64 v[36:37], 11, v[10:11]
	v_lshl_add_u64 v[12:13], s[0:1], 0, v[26:27]
	v_and_b32_e32 v0, 48, v0
	v_lshl_add_u64 v[4:5], s[0:1], 0, v[28:29]
	v_lshl_add_u64 v[6:7], s[0:1], 0, v[30:31]
	v_lshl_add_u64 v[2:3], s[0:1], 0, v[32:33]
	v_lshl_add_u64 v[8:9], s[4:5], 0, v[34:35]
	v_lshl_add_u64 v[10:11], s[4:5], 0, v[36:37]
	v_lshl_add_u64 v[38:39], v[12:13], 0, v[0:1]
	v_lshl_add_u64 v[40:41], v[4:5], 0, v[0:1]
	v_lshl_add_u64 v[42:43], v[6:7], 0, v[0:1]
	v_lshl_add_u64 v[44:45], v[2:3], 0, v[0:1]
	v_lshl_add_u64 v[46:47], v[8:9], 0, v[0:1]
	v_lshl_add_u64 v[48:49], v[10:11], 0, v[0:1]
	global_load_dwordx4 v[2:5], v[38:39], off
	global_load_dwordx4 v[6:9], v[40:41], off
	global_load_dwordx4 v[10:13], v[46:47], off
	global_load_dwordx4 v[14:17], v[48:49], off
	global_load_dwordx4 v[18:21], v[42:43], off
	global_load_dwordx4 v[22:25], v[44:45], off
	v_lshrrev_b32_e32 v51, 4, v169
	v_xor_b32_e32 v52, v51, v169
	v_lshlrev_b32_e32 v50, 5, v50
	v_lshlrev_b32_e32 v52, 3, v52
	v_and_or_b32 v184, v52, 24, v50
	v_lshlrev_b32_e32 v183, 1, v184
	s_waitcnt lgkmcnt(0)
	s_barrier
	v_and_b32_e32 v171, 0xffffff80, v169
	s_movk_i32 s0, 0xf1e0
	v_or_b32_e32 v32, v32, v0
	v_or_b32_e32 v30, v30, v0
	v_or_b32_e32 v28, v28, v0
	v_or_b32_e32 v26, v26, v0
	v_and_b32_e32 v168, 15, v169
	v_bfe_u32 v170, v169, 6, 1
	s_mov_b32 s10, 1
	v_lshlrev_b32_e32 v181, 12, v170
	v_lshlrev_b32_e32 v182, 6, v168
	s_waitcnt vmcnt(0)
	ds_write_b128 v183, v[2:5]
	ds_write_b128 v183, v[6:9] offset:4096
	ds_write_b128 v183, v[10:13] offset:16384
	ds_write_b128 v183, v[14:17] offset:20480
	ds_write_b128 v183, v[18:21] offset:8192
	ds_write_b128 v183, v[22:25] offset:12288
	global_load_dwordx4 v[132:135], v[38:39], off offset:64
	global_load_dwordx4 v[136:139], v[40:41], off offset:64
	global_load_dwordx4 v[140:143], v[42:43], off offset:64
	global_load_dwordx4 v[144:147], v[44:45], off offset:64
	global_load_dwordx4 v[148:151], v[46:47], off offset:64
	global_load_dwordx4 v[152:155], v[48:49], off offset:64
	v_lshrrev_b32_e32 v2, 2, v169
	v_xor_b32_e32 v2, v51, v2
	v_lshlrev_b32_e32 v2, 3, v2
	v_and_b32_e32 v180, 24, v2
	v_lshlrev_b32_e32 v2, 5, v169
	v_and_or_b32 v179, v2, s0, v180
	v_add_u32_e32 v2, 0xfffffeff, v171
	v_cmp_gt_i32_e32 vcc, -16, v2
	s_add_u32 s0, s8, 0x80
	v_mad_i64_i32 v[2:3], s[4:5], s12, v201, v[36:37]
	s_addc_u32 s1, s9, 0
	v_or_b32_e32 v2, v2, v0
	v_lshl_add_u64 v[156:157], s[0:1], 0, v[2:3]
	v_mad_i64_i32 v[2:3], s[4:5], s12, v201, v[34:35]
	v_or_b32_e32 v2, v2, v0
	v_lshl_add_u64 v[158:159], s[0:1], 0, v[2:3]
	s_add_u32 s0, s8, 0x1b2d6180
	s_addc_u32 s1, s9, 0
	v_mov_b32_e32 v2, v1
	v_mov_b32_e32 v3, v1
	v_lshl_add_u64 v[160:161], s[0:1], 0, v[32:33]
	v_lshl_add_u64 v[162:163], s[0:1], 0, v[30:31]
	v_lshl_add_u64 v[164:165], s[0:1], 0, v[28:29]
	v_lshl_add_u64 v[166:167], s[0:1], 0, v[26:27]
	v_mov_b32_e32 v0, v1
	v_mov_b64_e32 v[18:19], v[2:3]
	v_mov_b64_e32 v[6:7], v[2:3]
	v_mov_b64_e32 v[10:11], v[2:3]
	v_mov_b64_e32 v[14:15], v[2:3]
	v_mov_b64_e32 v[34:35], v[2:3]
	v_mov_b64_e32 v[22:23], v[2:3]
	v_mov_b64_e32 v[26:27], v[2:3]
	v_mov_b64_e32 v[30:31], v[2:3]
	v_mov_b64_e32 v[50:51], v[2:3]
	v_mov_b64_e32 v[38:39], v[2:3]
	v_mov_b64_e32 v[42:43], v[2:3]
	v_mov_b64_e32 v[46:47], v[2:3]
	v_mov_b64_e32 v[66:67], v[2:3]
	v_mov_b64_e32 v[54:55], v[2:3]
	v_mov_b64_e32 v[58:59], v[2:3]
	v_mov_b64_e32 v[62:63], v[2:3]
	v_mov_b64_e32 v[82:83], v[2:3]
	v_mov_b64_e32 v[70:71], v[2:3]
	v_mov_b64_e32 v[74:75], v[2:3]
	v_mov_b64_e32 v[78:79], v[2:3]
	v_mov_b64_e32 v[98:99], v[2:3]
	v_mov_b64_e32 v[86:87], v[2:3]
	v_mov_b64_e32 v[90:91], v[2:3]
	v_mov_b64_e32 v[94:95], v[2:3]
	v_mov_b64_e32 v[114:115], v[2:3]
	v_mov_b64_e32 v[102:103], v[2:3]
	v_mov_b64_e32 v[106:107], v[2:3]
	v_mov_b64_e32 v[110:111], v[2:3]
	v_mov_b64_e32 v[130:131], v[2:3]
	v_mov_b64_e32 v[118:119], v[2:3]
	v_mov_b64_e32 v[122:123], v[2:3]
	v_mov_b64_e32 v[126:127], v[2:3]
	s_mov_b64 s[0:1], 0
	v_mov_b64_e32 v[16:17], v[0:1]
	v_mov_b64_e32 v[4:5], v[0:1]
	v_mov_b64_e32 v[8:9], v[0:1]
	v_mov_b64_e32 v[12:13], v[0:1]
	v_mov_b64_e32 v[32:33], v[0:1]
	v_mov_b64_e32 v[20:21], v[0:1]
	v_mov_b64_e32 v[24:25], v[0:1]
	v_mov_b64_e32 v[28:29], v[0:1]
	v_mov_b64_e32 v[48:49], v[0:1]
	v_mov_b64_e32 v[36:37], v[0:1]
	v_mov_b64_e32 v[40:41], v[0:1]
	v_mov_b64_e32 v[44:45], v[0:1]
	v_mov_b64_e32 v[64:65], v[0:1]
	v_mov_b64_e32 v[52:53], v[0:1]
	v_mov_b64_e32 v[56:57], v[0:1]
	v_mov_b64_e32 v[60:61], v[0:1]
	v_mov_b64_e32 v[80:81], v[0:1]
	v_mov_b64_e32 v[68:69], v[0:1]
	v_mov_b64_e32 v[72:73], v[0:1]
	v_mov_b64_e32 v[76:77], v[0:1]
	v_mov_b64_e32 v[96:97], v[0:1]
	v_mov_b64_e32 v[84:85], v[0:1]
	v_mov_b64_e32 v[88:89], v[0:1]
	v_mov_b64_e32 v[92:93], v[0:1]
	v_mov_b64_e32 v[112:113], v[0:1]
	v_mov_b64_e32 v[100:101], v[0:1]
	v_mov_b64_e32 v[104:105], v[0:1]
	v_mov_b64_e32 v[108:109], v[0:1]
	v_mov_b64_e32 v[128:129], v[0:1]
	v_mov_b64_e32 v[116:117], v[0:1]
	v_mov_b64_e32 v[120:121], v[0:1]
	v_mov_b64_e32 v[124:125], v[0:1]
	s_waitcnt lgkmcnt(0)
	s_barrier
	s_cmp_eq_u64 vcc, exec
	s_cbranch_scc1 .Lp1_fk
	s_branch .LBB0_297
; template <int K, class FA, class FB, class Epi>
; __device__ __forceinline__ void gemm_tile(char* smem, int nvalid_rows, FA rowA, FB rowB, Epi epi) {
;     ...
;   for (int kt = 0; kt < NK; ++kt) {
;     const u16* Bc = (const u16*)(smem + (kt & 1) * 24576);
;     bf16x8 Bt[4];
; #pragma unroll
;     for (int n = 0; n < 4; ++n) Bt[n] = *(const bf16x8*)&Bc[rdB + n * 16 * 32];
;     if (msub > 0) {
;       bf16x8 At[4];
; #pragma unroll
;       for (int m = 0; m < 4; ++m) At[m] = *(const bf16x8*)&Bc[rdA + m * 16 * 32];
;       __builtin_amdgcn_s_setprio(1);
; #pragma unroll
;       for (int m = 0; m < 4; ++m)
; #pragma unroll
;         for (int n = 0; n < 4; ++n) acc[m][n] = __builtin_amdgcn_mfma_f32_16x16x32_bf16(At[m], Bt[n], acc[m][n], 0, 0, 0);
;       __builtin_amdgcn_s_setprio(0);
;     }
;     if (msub > 4) {
;       bf16x8 At[4];
; #pragma unroll
;       for (int m = 0; m < 4; ++m) At[m] = *(const bf16x8*)&Bc[rdA + (m + 4) * 16 * 32];
;       __builtin_amdgcn_s_setprio(1);
; #pragma unroll
;       for (int m = 0; m < 4; ++m)
; #pragma unroll
;         for (int n = 0; n < 4; ++n) acc[m + 4][n] = __builtin_amdgcn_mfma_f32_16x16x32_bf16(At[m], Bt[n], acc[m + 4][n], 0, 0, 0);
;       __builtin_amdgcn_s_setprio(0);
;     }
;     if (kt + 1 < NK) {
;       u16* Bn = (u16*)(smem + ((kt + 1) & 1) * 24576);
;       *(uint4*)&Bn[wofsA] = ra0; *(uint4*)&Bn[wofsA + 64 * 32] = ra1;
;       *(uint4*)&Bn[wofsA + 128 * 32] = ra2; *(uint4*)&Bn[wofsA + 192 * 32] = ra3;
;       *(uint4*)&Bn[wofsB] = rb0; *(uint4*)&Bn[wofsB + 64 * 32] = rb1;
;     }
;     if (kt + 2 < NK) {
;       const int ko = (kt + 2) * 32;
;       ra0 = *(const uint4*)(pa0 + ko); ra1 = *(const uint4*)(pa1 + ko); ra2 = *(const uint4*)(pa2 + ko); ra3 = *(const uint4*)(pa3 + ko);
;       rb0 = *(const uint4*)(pb0 + ko); rb1 = *(const uint4*)(pb1 + ko);
;     }
;     __syncthreads();
;   }
.Lp1_fk:
	s_bitcmp1_b32 s10, 0
	s_cselect_b32 s11, 0, 0x6000
	v_or_b32_e32 v0, s11, v181
	v_lshlrev_b32_e32 v2, 1, v180
	v_add3_u32 v0, v0, v182, v2
	ds_read_b128 v[186:189], v0 offset:19456
	ds_read_b128 v[190:193], v0 offset:18432
	ds_read_b128 v[212:215], v0 offset:17408
	ds_read_b128 v[216:219], v0 offset:16384
	v_lshl_add_u32 v0, v179, 1, s11
	ds_read_b128 v[220:223], v0
	ds_read_b128 v[224:227], v0 offset:1024
	ds_read_b128 v[228:231], v0 offset:2048
	ds_read_b128 v[232:235], v0 offset:3072
	s_setprio 1
	s_waitcnt lgkmcnt(0)
	v_mfma_f32_16x16x32_bf16 v[124:127], v[220:223], v[216:219], v[124:127]
	v_mfma_f32_16x16x32_bf16 v[120:123], v[220:223], v[212:215], v[120:123]
	v_mfma_f32_16x16x32_bf16 v[116:119], v[220:223], v[190:193], v[116:119]
	v_mfma_f32_16x16x32_bf16 v[128:131], v[220:223], v[186:189], v[128:131]
	v_mfma_f32_16x16x32_bf16 v[108:111], v[224:227], v[216:219], v[108:111]
	v_mfma_f32_16x16x32_bf16 v[104:107], v[224:227], v[212:215], v[104:107]
	v_mfma_f32_16x16x32_bf16 v[100:103], v[224:227], v[190:193], v[100:103]
	v_mfma_f32_16x16x32_bf16 v[112:115], v[224:227], v[186:189], v[112:115]
	v_mfma_f32_16x16x32_bf16 v[92:95], v[228:231], v[216:219], v[92:95]
	v_mfma_f32_16x16x32_bf16 v[88:91], v[228:231], v[212:215], v[88:91]
	v_mfma_f32_16x16x32_bf16 v[84:87], v[228:231], v[190:193], v[84:87]
	v_mfma_f32_16x16x32_bf16 v[96:99], v[228:231], v[186:189], v[96:99]
	v_mfma_f32_16x16x32_bf16 v[76:79], v[232:235], v[216:219], v[76:79]
	v_mfma_f32_16x16x32_bf16 v[72:75], v[232:235], v[212:215], v[72:75]
	v_mfma_f32_16x16x32_bf16 v[68:71], v[232:235], v[190:193], v[68:71]
	v_mfma_f32_16x16x32_bf16 v[80:83], v[232:235], v[186:189], v[80:83]
	s_setprio 0
	ds_read_b128 v[220:223], v0 offset:4096
	ds_read_b128 v[224:227], v0 offset:5120
	ds_read_b128 v[228:231], v0 offset:6144
	ds_read_b128 v[232:235], v0 offset:7168
	s_setprio 1
	s_waitcnt lgkmcnt(0)
	v_mfma_f32_16x16x32_bf16 v[60:63], v[220:223], v[216:219], v[60:63]
	v_mfma_f32_16x16x32_bf16 v[56:59], v[220:223], v[212:215], v[56:59]
	v_mfma_f32_16x16x32_bf16 v[52:55], v[220:223], v[190:193], v[52:55]
	v_mfma_f32_16x16x32_bf16 v[64:67], v[220:223], v[186:189], v[64:67]
	v_mfma_f32_16x16x32_bf16 v[44:47], v[224:227], v[216:219], v[44:47]
	v_mfma_f32_16x16x32_bf16 v[40:43], v[224:227], v[212:215], v[40:43]
	v_mfma_f32_16x16x32_bf16 v[36:39], v[224:227], v[190:193], v[36:39]
	v_mfma_f32_16x16x32_bf16 v[48:51], v[224:227], v[186:189], v[48:51]
	v_mfma_f32_16x16x32_bf16 v[28:31], v[228:231], v[216:219], v[28:31]
	v_mfma_f32_16x16x32_bf16 v[24:27], v[228:231], v[212:215], v[24:27]
	v_mfma_f32_16x16x32_bf16 v[20:23], v[228:231], v[190:193], v[20:23]
	v_mfma_f32_16x16x32_bf16 v[32:35], v[228:231], v[186:189], v[32:35]
	v_mfma_f32_16x16x32_bf16 v[12:15], v[232:235], v[216:219], v[12:15]
	v_mfma_f32_16x16x32_bf16 v[8:11], v[232:235], v[212:215], v[8:11]
	v_mfma_f32_16x16x32_bf16 v[4:7], v[232:235], v[190:193], v[4:7]
	v_mfma_f32_16x16x32_bf16 v[16:19], v[232:235], v[186:189], v[16:19]
	s_setprio 0
	s_bitcmp1_b32 s10, 0
	s_cselect_b32 s4, 0x6000, 0
	v_lshl_add_u32 v0, v184, 1, s4
	s_waitcnt vmcnt(0)
	ds_write_b128 v0, v[132:135]
	ds_write_b128 v0, v[136:139] offset:4096
	ds_write_b128 v0, v[140:143] offset:8192
	ds_write_b128 v0, v[144:147] offset:12288
	ds_write_b128 v0, v[148:151] offset:16384
	ds_write_b128 v0, v[152:155] offset:20480
	v_lshl_add_u64 v[2:3], v[166:167], 0, s[0:1]
	v_lshl_add_u64 v[136:137], v[164:165], 0, s[0:1]
	global_load_dwordx4 v[132:135], v[2:3], off
	s_nop 0
	global_load_dwordx4 v[136:139], v[136:137], off
	v_lshl_add_u64 v[2:3], v[162:163], 0, s[0:1]
	v_lshl_add_u64 v[144:145], v[160:161], 0, s[0:1]
	global_load_dwordx4 v[140:143], v[2:3], off
	s_nop 0
	global_load_dwordx4 v[144:147], v[144:145], off
	v_lshl_add_u64 v[2:3], v[158:159], 0, s[0:1]
	v_lshl_add_u64 v[152:153], v[156:157], 0, s[0:1]
	global_load_dwordx4 v[148:151], v[2:3], off
	s_nop 0
	global_load_dwordx4 v[152:155], v[152:153], off
	s_add_u32 s0, s0, 64
	s_addc_u32 s1, s1, 0
	s_add_i32 s10, s10, 1
	s_cmpk_eq_i32 s0, 0x780
	s_waitcnt lgkmcnt(0)
	s_barrier
	s_cbranch_scc0 .Lp1_fk
	s_branch .LBB0_299

; __device__ __forceinline__ int vtid() { int t = threadIdx.x; asm volatile("" : "+v"(t)); return t; }
; template <int K, class FA, class FB, class Epi>
; __device__ __forceinline__ void gemm_tile(char* smem, int nvalid_rows, FA rowA, FB rowB, Epi epi) {
;   const int tid = vtid(), lane = tid & 63, wid = tid >> 6, wr = wid >> 1, wc = wid & 1, fr = lane & 15, fq = lane >> 4;
;   const int seg = tid & 3, r0 = tid >> 2;
;   int msub = (nvalid_rows - wr * 128 + 15) >> 4;
;   msub = msub < 0 ? 0 : (msub > 8 ? 8 : msub);
;   const u16* pa0 = rowA(r0) + seg * 8;
;   const u16* pa1 = rowA(r0 + 64) + seg * 8;
;   const u16* pa2 = rowA(r0 + 128) + seg * 8;
;   const u16* pa3 = rowA(r0 + 192) + seg * 8;
;   const u16* pb0 = rowB(r0) + seg * 8;
;   const u16* pb1 = rowB(r0 + 64) + seg * 8;
;   f32x4 acc[8][4];
; #pragma unroll
;   for (int m = 0; m < 8; ++m)
; #pragma unroll
;     for (int n = 0; n < 4; ++n) acc[m][n] = (f32x4){0.f, 0.f, 0.f, 0.f};
;   uint4 ra0, ra1, ra2, ra3, rb0, rb1;
;   ra0 = *(const uint4*)pa0; ra1 = *(const uint4*)pa1; ra2 = *(const uint4*)pa2; ra3 = *(const uint4*)pa3;
;   rb0 = *(const uint4*)pb0; rb1 = *(const uint4*)pb1;
;   constexpr int NK = K / 32;
;   const int wsw = (seg ^ ((r0 >> 2) & 3)) * 8;
;   const int wofsA = r0 * 32 + wsw, wofsB = 256 * 32 + r0 * 32 + wsw;
;   __syncthreads();
;   {
;     u16* B0 = (u16*)smem;
;     *(uint4*)&B0[wofsA] = ra0; *(uint4*)&B0[wofsA + 64 * 32] = ra1;
;     *(uint4*)&B0[wofsA + 128 * 32] = ra2; *(uint4*)&B0[wofsA + 192 * 32] = ra3;
;     *(uint4*)&B0[wofsB] = rb0; *(uint4*)&B0[wofsB + 64 * 32] = rb1;
;   }
;   ra0 = *(const uint4*)(pa0 + 32); ra1 = *(const uint4*)(pa1 + 32); ra2 = *(const uint4*)(pa2 + 32); ra3 = *(const uint4*)(pa3 + 32);
;   rb0 = *(const uint4*)(pb0 + 32); rb1 = *(const uint4*)(pb1 + 32);
;   __syncthreads();
;   const int rsw = (fq ^ ((fr >> 2) & 3)) * 8;
;   const int rdA = (wr * 128 + fr) * 32 + rsw, rdB = 256 * 32 + (wc * 64 + fr) * 32 + rsw;
; __device__ __forceinline__ void outproj_tile(const Params& p, char* smem, int l, int mt, int nt, int ks) {
;     ...
;   auto rowA = [&](int r) { return MIX + (size_t)(mt * 256 + r) * 1024 + koff; };
;   auto rowB = [&](int r) { return W + (size_t)(nt * 128 + r) * 1024 + koff; };
.LBB0_1214:
	s_and_b64 vcc, exec, s[14:15]
	s_cbranch_vccz .LBB0_1194
	s_ashr_i32 s12, s17, 3
	s_waitcnt vmcnt(0)
	v_mov_b32_e32 v27, v172
	s_lshl_b32 s2, s12, 8
	v_ashrrev_i32_e32 v26, 2, v27
	v_add_u32_e32 v2, s2, v26
	v_ashrrev_i32_e32 v3, 31, v2
	v_add_u32_e32 v0, 64, v26
	s_lshl_b32 s14, s19, 7
	v_lshlrev_b64 v[28:29], 11, v[2:3]
	v_add_u32_e32 v4, s2, v0
	v_add_u32_e32 v6, 0x80, v2
	v_add_u32_e32 v2, 0xc0, v2
	v_add_u32_e32 v8, s14, v26
	v_add_u32_e32 v10, s14, v0
	v_ashrrev_i32_e32 v5, 31, v4
	v_ashrrev_i32_e32 v7, 31, v6
	v_ashrrev_i32_e32 v3, 31, v2
	v_ashrrev_i32_e32 v9, 31, v8
	v_ashrrev_i32_e32 v11, 31, v10
	v_lshlrev_b32_e32 v0, 4, v27
	v_lshlrev_b64 v[30:31], 11, v[4:5]
	v_lshlrev_b64 v[32:33], 11, v[6:7]
	v_lshlrev_b64 v[34:35], 11, v[2:3]
	v_lshlrev_b64 v[8:9], 11, v[8:9]
	v_lshlrev_b64 v[36:37], 11, v[10:11]
	v_lshl_add_u64 v[12:13], s[8:9], 0, v[28:29]
	v_and_b32_e32 v38, 48, v0
	v_mov_b32_e32 v39, v1
	v_lshl_add_u64 v[4:5], s[8:9], 0, v[30:31]
	v_lshl_add_u64 v[6:7], s[8:9], 0, v[32:33]
	v_lshl_add_u64 v[2:3], s[8:9], 0, v[34:35]
	v_lshl_add_u64 v[8:9], s[10:11], 0, v[8:9]
	v_lshl_add_u64 v[10:11], s[10:11], 0, v[36:37]
	v_lshl_add_u64 v[40:41], v[12:13], 0, v[38:39]
	v_lshl_add_u64 v[42:43], v[4:5], 0, v[38:39]
	v_lshl_add_u64 v[44:45], v[6:7], 0, v[38:39]
	v_lshl_add_u64 v[46:47], v[2:3], 0, v[38:39]
	v_lshl_add_u64 v[48:49], v[8:9], 0, v[38:39]
	v_lshl_add_u64 v[50:51], v[10:11], 0, v[38:39]
	global_load_dwordx4 v[2:5], v[40:41], off
	global_load_dwordx4 v[6:9], v[48:49], off
	global_load_dwordx4 v[10:13], v[42:43], off
	global_load_dwordx4 v[14:17], v[44:45], off
	global_load_dwordx4 v[18:21], v[46:47], off
	global_load_dwordx4 v[22:25], v[50:51], off
	v_lshrrev_b32_e32 v157, 4, v27
	v_xor_b32_e32 v0, v157, v27
	v_lshlrev_b32_e32 v52, 5, v26
	v_lshlrev_b32_e32 v0, 3, v0
	v_and_or_b32 v170, v0, 24, v52
	v_lshlrev_b32_e32 v169, 1, v170
	s_waitcnt lgkmcnt(0)
	s_barrier
	s_movk_i32 s8, 0xf1e0
	v_and_b32_e32 v168, 0xffffff80, v27
	v_and_b32_e32 v156, 15, v27
	v_bfe_u32 v0, v27, 6, 1
	v_or_b32_e32 v34, v34, v38
	v_or_b32_e32 v32, v32, v38
	v_or_b32_e32 v30, v30, v38
	v_or_b32_e32 v28, v28, v38
	s_mov_b32 s10, 1
	v_lshlrev_b32_e32 v180, 12, v0
	v_lshlrev_b32_e32 v181, 6, v156
	s_waitcnt vmcnt(0)
	ds_write_b128 v169, v[2:5]
	ds_write_b128 v169, v[6:9] offset:16384
	ds_write_b128 v169, v[10:13] offset:4096
	ds_write_b128 v169, v[14:17] offset:8192
	ds_write_b128 v169, v[18:21] offset:12288
	ds_write_b128 v169, v[22:25] offset:20480
	global_load_dwordx4 v[132:135], v[40:41], off offset:64
	global_load_dwordx4 v[136:139], v[42:43], off offset:64
	global_load_dwordx4 v[140:143], v[44:45], off offset:64
	global_load_dwordx4 v[144:147], v[46:47], off offset:64
	global_load_dwordx4 v[148:151], v[48:49], off offset:64
	global_load_dwordx4 v[152:155], v[50:51], off offset:64
	v_lshrrev_b32_e32 v2, 2, v27
	v_xor_b32_e32 v2, v157, v2
	v_lshlrev_b32_e32 v2, 3, v2
	v_and_b32_e32 v171, 24, v2
	v_lshlrev_b32_e32 v2, 5, v27
	v_and_or_b32 v179, v2, s8, v171
	s_add_u32 s8, s0, 0xa00080
	v_add_u32_e32 v2, 0xfffffeff, v168
	s_addc_u32 s9, s1, 0
	s_lshl_b32 s11, s19, 18
	v_cmp_gt_i32_e32 vcc, -16, v2
	v_lshl_add_u64 v[2:3], s[6:7], 0, v[36:37]
	s_add_u32 s6, s6, s11
	v_ashrrev_i32_e32 v27, 31, v26
	s_addc_u32 s7, s7, 0
	v_lshlrev_b64 v[4:5], 11, v[26:27]
	v_lshl_add_u64 v[4:5], s[6:7], 0, v[4:5]
	s_add_u32 s6, s0, 0x28096180
	v_lshl_add_u64 v[4:5], v[4:5], 0, v[38:39]
	s_addc_u32 s7, s1, 0
	v_mov_b32_e32 v6, v1
	v_mov_b32_e32 v7, v1
	v_lshl_add_u64 v[2:3], v[2:3], 0, v[38:39]
	v_lshl_add_u64 v[158:159], s[8:9], 0, v[4:5]
	v_lshl_add_u64 v[160:161], s[6:7], 0, v[34:35]
	v_lshl_add_u64 v[162:163], s[6:7], 0, v[32:33]
	v_lshl_add_u64 v[164:165], s[6:7], 0, v[30:31]
	v_lshl_add_u64 v[166:167], s[6:7], 0, v[28:29]
	v_mov_b32_e32 v4, v1
	v_mov_b32_e32 v5, v1
	v_mov_b64_e32 v[10:11], v[6:7]
	v_mov_b64_e32 v[14:15], v[6:7]
	v_mov_b64_e32 v[18:19], v[6:7]
	v_mov_b64_e32 v[22:23], v[6:7]
	v_mov_b64_e32 v[26:27], v[6:7]
	v_mov_b64_e32 v[30:31], v[6:7]
	v_mov_b64_e32 v[34:35], v[6:7]
	v_mov_b64_e32 v[38:39], v[6:7]
	v_mov_b64_e32 v[42:43], v[6:7]
	v_mov_b64_e32 v[46:47], v[6:7]
	v_mov_b64_e32 v[50:51], v[6:7]
	v_mov_b64_e32 v[54:55], v[6:7]
	v_mov_b64_e32 v[58:59], v[6:7]
	v_mov_b64_e32 v[62:63], v[6:7]
	v_mov_b64_e32 v[66:67], v[6:7]
	v_mov_b64_e32 v[70:71], v[6:7]
	v_mov_b64_e32 v[74:75], v[6:7]
	v_mov_b64_e32 v[78:79], v[6:7]
	v_mov_b64_e32 v[82:83], v[6:7]
	v_mov_b64_e32 v[86:87], v[6:7]
	v_mov_b64_e32 v[90:91], v[6:7]
	v_mov_b64_e32 v[94:95], v[6:7]
	v_mov_b64_e32 v[98:99], v[6:7]
	v_mov_b64_e32 v[102:103], v[6:7]
	v_mov_b64_e32 v[106:107], v[6:7]
	v_mov_b64_e32 v[110:111], v[6:7]
	v_mov_b64_e32 v[114:115], v[6:7]
	v_mov_b64_e32 v[118:119], v[6:7]
	v_mov_b64_e32 v[122:123], v[6:7]
	v_mov_b64_e32 v[126:127], v[6:7]
	v_mov_b64_e32 v[130:131], v[6:7]
	v_lshl_add_u64 v[2:3], s[8:9], 0, v[2:3]
	s_mov_b64 s[6:7], 0
	v_mov_b64_e32 v[8:9], v[4:5]
	v_mov_b64_e32 v[12:13], v[4:5]
	v_mov_b64_e32 v[16:17], v[4:5]
	v_mov_b64_e32 v[20:21], v[4:5]
	v_mov_b64_e32 v[24:25], v[4:5]
	v_mov_b64_e32 v[28:29], v[4:5]
	v_mov_b64_e32 v[32:33], v[4:5]
	v_mov_b64_e32 v[36:37], v[4:5]
	v_mov_b64_e32 v[40:41], v[4:5]
	v_mov_b64_e32 v[44:45], v[4:5]
	v_mov_b64_e32 v[48:49], v[4:5]
	v_mov_b64_e32 v[52:53], v[4:5]
	v_mov_b64_e32 v[56:57], v[4:5]
	v_mov_b64_e32 v[60:61], v[4:5]
	v_mov_b64_e32 v[64:65], v[4:5]
	v_mov_b64_e32 v[68:69], v[4:5]
	v_mov_b64_e32 v[72:73], v[4:5]
	v_mov_b64_e32 v[76:77], v[4:5]
	v_mov_b64_e32 v[80:81], v[4:5]
	v_mov_b64_e32 v[84:85], v[4:5]
	v_mov_b64_e32 v[88:89], v[4:5]
	v_mov_b64_e32 v[92:93], v[4:5]
	v_mov_b64_e32 v[96:97], v[4:5]
	v_mov_b64_e32 v[100:101], v[4:5]
	v_mov_b64_e32 v[104:105], v[4:5]
	v_mov_b64_e32 v[108:109], v[4:5]
	v_mov_b64_e32 v[112:113], v[4:5]
	v_mov_b64_e32 v[116:117], v[4:5]
	v_mov_b64_e32 v[120:121], v[4:5]
	v_mov_b64_e32 v[124:125], v[4:5]
	v_mov_b64_e32 v[128:129], v[4:5]
	s_waitcnt lgkmcnt(0)
	s_barrier
	s_cmp_eq_u64 vcc, exec
	s_cbranch_scc1 .Lp3_fk
	s_branch .LBB0_1217
; template <int K, class FA, class FB, class Epi>
; __device__ __forceinline__ void gemm_tile(char* smem, int nvalid_rows, FA rowA, FB rowB, Epi epi) {
;     ...
;   for (int kt = 0; kt < NK; ++kt) {
;     const u16* Bc = (const u16*)(smem + (kt & 1) * 24576);
;     bf16x8 Bt[4];
; #pragma unroll
;     for (int n = 0; n < 4; ++n) Bt[n] = *(const bf16x8*)&Bc[rdB + n * 16 * 32];
;     if (msub > 0) {
;       bf16x8 At[4];
; #pragma unroll
;       for (int m = 0; m < 4; ++m) At[m] = *(const bf16x8*)&Bc[rdA + m * 16 * 32];
;       __builtin_amdgcn_s_setprio(1);
; #pragma unroll
;       for (int m = 0; m < 4; ++m)
; #pragma unroll
;         for (int n = 0; n < 4; ++n) acc[m][n] = __builtin_amdgcn_mfma_f32_16x16x32_bf16(At[m], Bt[n], acc[m][n], 0, 0, 0);
;       __builtin_amdgcn_s_setprio(0);
;     }
;     if (msub > 4) {
;       bf16x8 At[4];
; #pragma unroll
;       for (int m = 0; m < 4; ++m) At[m] = *(const bf16x8*)&Bc[rdA + (m + 4) * 16 * 32];
;       __builtin_amdgcn_s_setprio(1);
; #pragma unroll
;       for (int m = 0; m < 4; ++m)
; #pragma unroll
;         for (int n = 0; n < 4; ++n) acc[m + 4][n] = __builtin_amdgcn_mfma_f32_16x16x32_bf16(At[m], Bt[n], acc[m + 4][n], 0, 0, 0);
;       __builtin_amdgcn_s_setprio(0);
;     }
;     if (kt + 1 < NK) {
;       u16* Bn = (u16*)(smem + ((kt + 1) & 1) * 24576);
;       *(uint4*)&Bn[wofsA] = ra0; *(uint4*)&Bn[wofsA + 64 * 32] = ra1;
;       *(uint4*)&Bn[wofsA + 128 * 32] = ra2; *(uint4*)&Bn[wofsA + 192 * 32] = ra3;
;       *(uint4*)&Bn[wofsB] = rb0; *(uint4*)&Bn[wofsB + 64 * 32] = rb1;
;     }
;     if (kt + 2 < NK) {
;       const int ko = (kt + 2) * 32;
;       ra0 = *(const uint4*)(pa0 + ko); ra1 = *(const uint4*)(pa1 + ko); ra2 = *(const uint4*)(pa2 + ko); ra3 = *(const uint4*)(pa3 + ko);
;       rb0 = *(const uint4*)(pb0 + ko); rb1 = *(const uint4*)(pb1 + ko);
;     }
;     __syncthreads();
;   }
.Lp3_fk:
	s_bitcmp1_b32 s10, 0
	s_cselect_b32 s11, 0, 0x6000
	v_or_b32_e32 v182, s11, v180
	v_lshlrev_b32_e32 v183, 1, v171
	v_add3_u32 v211, v182, v181, v183
	ds_read_b128 v[182:185], v211 offset:19456
	ds_read_b128 v[186:189], v211 offset:18432
	ds_read_b128 v[190:193], v211 offset:17408
	ds_read_b128 v[212:215], v211 offset:16384
	v_lshl_add_u32 v211, v179, 1, s11
	ds_read_b128 v[216:219], v211
	ds_read_b128 v[220:223], v211 offset:1024
	ds_read_b128 v[224:227], v211 offset:2048
	ds_read_b128 v[228:231], v211 offset:3072
	s_setprio 1
	s_waitcnt lgkmcnt(0)
	v_mfma_f32_16x16x32_bf16 v[128:131], v[216:219], v[212:215], v[128:131]
	v_mfma_f32_16x16x32_bf16 v[124:127], v[216:219], v[190:193], v[124:127]
	v_mfma_f32_16x16x32_bf16 v[120:123], v[216:219], v[186:189], v[120:123]
	v_mfma_f32_16x16x32_bf16 v[116:119], v[216:219], v[182:185], v[116:119]
	v_mfma_f32_16x16x32_bf16 v[112:115], v[220:223], v[212:215], v[112:115]
	v_mfma_f32_16x16x32_bf16 v[108:111], v[220:223], v[190:193], v[108:111]
	v_mfma_f32_16x16x32_bf16 v[104:107], v[220:223], v[186:189], v[104:107]
	v_mfma_f32_16x16x32_bf16 v[100:103], v[220:223], v[182:185], v[100:103]
	v_mfma_f32_16x16x32_bf16 v[96:99], v[224:227], v[212:215], v[96:99]
	v_mfma_f32_16x16x32_bf16 v[92:95], v[224:227], v[190:193], v[92:95]
	v_mfma_f32_16x16x32_bf16 v[88:91], v[224:227], v[186:189], v[88:91]
	v_mfma_f32_16x16x32_bf16 v[84:87], v[224:227], v[182:185], v[84:87]
	v_mfma_f32_16x16x32_bf16 v[80:83], v[228:231], v[212:215], v[80:83]
	v_mfma_f32_16x16x32_bf16 v[76:79], v[228:231], v[190:193], v[76:79]
	v_mfma_f32_16x16x32_bf16 v[72:75], v[228:231], v[186:189], v[72:75]
	v_mfma_f32_16x16x32_bf16 v[68:71], v[228:231], v[182:185], v[68:71]
	s_setprio 0
	ds_read_b128 v[216:219], v211 offset:4096
	ds_read_b128 v[220:223], v211 offset:5120
	ds_read_b128 v[224:227], v211 offset:6144
	ds_read_b128 v[228:231], v211 offset:7168
	s_setprio 1
	s_waitcnt lgkmcnt(0)
	v_mfma_f32_16x16x32_bf16 v[64:67], v[216:219], v[212:215], v[64:67]
	v_mfma_f32_16x16x32_bf16 v[60:63], v[216:219], v[190:193], v[60:63]
	v_mfma_f32_16x16x32_bf16 v[56:59], v[216:219], v[186:189], v[56:59]
	v_mfma_f32_16x16x32_bf16 v[52:55], v[216:219], v[182:185], v[52:55]
	v_mfma_f32_16x16x32_bf16 v[48:51], v[220:223], v[212:215], v[48:51]
	v_mfma_f32_16x16x32_bf16 v[44:47], v[220:223], v[190:193], v[44:47]
	v_mfma_f32_16x16x32_bf16 v[40:43], v[220:223], v[186:189], v[40:43]
	v_mfma_f32_16x16x32_bf16 v[36:39], v[220:223], v[182:185], v[36:39]
	v_mfma_f32_16x16x32_bf16 v[32:35], v[224:227], v[212:215], v[32:35]
	v_mfma_f32_16x16x32_bf16 v[28:31], v[224:227], v[190:193], v[28:31]
	v_mfma_f32_16x16x32_bf16 v[24:27], v[224:227], v[186:189], v[24:27]
	v_mfma_f32_16x16x32_bf16 v[20:23], v[224:227], v[182:185], v[20:23]
	v_mfma_f32_16x16x32_bf16 v[16:19], v[228:231], v[212:215], v[16:19]
	v_mfma_f32_16x16x32_bf16 v[12:15], v[228:231], v[190:193], v[12:15]
	v_mfma_f32_16x16x32_bf16 v[8:11], v[228:231], v[186:189], v[8:11]
	v_mfma_f32_16x16x32_bf16 v[4:7], v[228:231], v[182:185], v[4:7]
	s_setprio 0
	s_bitcmp1_b32 s10, 0
	s_cselect_b32 s8, 0x6000, 0
	v_lshl_add_u32 v182, v170, 1, s8
	s_waitcnt vmcnt(0)
	ds_write_b128 v182, v[132:135]
	ds_write_b128 v182, v[136:139] offset:4096
	ds_write_b128 v182, v[140:143] offset:8192
	ds_write_b128 v182, v[144:147] offset:12288
	ds_write_b128 v182, v[148:151] offset:16384
	ds_write_b128 v182, v[152:155] offset:20480
	v_lshl_add_u64 v[132:133], v[166:167], 0, s[6:7]
	v_lshl_add_u64 v[136:137], v[164:165], 0, s[6:7]
	v_lshl_add_u64 v[140:141], v[162:163], 0, s[6:7]
	v_lshl_add_u64 v[144:145], v[160:161], 0, s[6:7]
	v_lshl_add_u64 v[148:149], v[158:159], 0, s[6:7]
	v_lshl_add_u64 v[152:153], v[2:3], 0, s[6:7]
	global_load_dwordx4 v[132:135], v[132:133], off
	s_nop 0
	global_load_dwordx4 v[136:139], v[136:137], off
	s_nop 0
	global_load_dwordx4 v[140:143], v[140:141], off
	s_nop 0
	global_load_dwordx4 v[144:147], v[144:145], off
	s_nop 0
	global_load_dwordx4 v[148:151], v[148:149], off
	s_nop 0
	global_load_dwordx4 v[152:155], v[152:153], off
	s_add_u32 s6, s6, 64
	s_addc_u32 s7, s7, 0
	s_add_i32 s10, s10, 1
	s_cmpk_eq_i32 s6, 0x780
	s_waitcnt lgkmcnt(0)
	s_barrier
	s_cbranch_scc0 .Lp3_fk
	s_branch .LBB0_1219

; template <int K, class FA, class FB, class Epi>
; __device__ __forceinline__ void gemm_tile(char* smem, int nvalid_rows, FA rowA, FB rowB, Epi epi) {
;   const int tid = vtid(), lane = tid & 63, wid = tid >> 6, wr = wid >> 1, wc = wid & 1, fr = lane & 15, fq = lane >> 4;
;   const int seg = tid & 3, r0 = tid >> 2;
;   int msub = (nvalid_rows - wr * 128 + 15) >> 4;
;   msub = msub < 0 ? 0 : (msub > 8 ? 8 : msub);
;   const u16* pa0 = rowA(r0) + seg * 8;
;   const u16* pa1 = rowA(r0 + 64) + seg * 8;
;   const u16* pa2 = rowA(r0 + 128) + seg * 8;
;   const u16* pa3 = rowA(r0 + 192) + seg * 8;
;   const u16* pb0 = rowB(r0) + seg * 8;
;   const u16* pb1 = rowB(r0 + 64) + seg * 8;
;   f32x4 acc[8][4];
; #pragma unroll
;   for (int m = 0; m < 8; ++m)
; #pragma unroll
;     for (int n = 0; n < 4; ++n) acc[m][n] = (f32x4){0.f, 0.f, 0.f, 0.f};
;   uint4 ra0, ra1, ra2, ra3, rb0, rb1;
;   ra0 = *(const uint4*)pa0; ra1 = *(const uint4*)pa1; ra2 = *(const uint4*)pa2; ra3 = *(const uint4*)pa3;
;   rb0 = *(const uint4*)pb0; rb1 = *(const uint4*)pb1;
;   constexpr int NK = K / 32;
;   const int wsw = (seg ^ ((r0 >> 2) & 3)) * 8;
;   const int wofsA = r0 * 32 + wsw, wofsB = 256 * 32 + r0 * 32 + wsw;
;   __syncthreads();
;   {
;     u16* B0 = (u16*)smem;
;     *(uint4*)&B0[wofsA] = ra0; *(uint4*)&B0[wofsA + 64 * 32] = ra1;
;     *(uint4*)&B0[wofsA + 128 * 32] = ra2; *(uint4*)&B0[wofsA + 192 * 32] = ra3;
;     *(uint4*)&B0[wofsB] = rb0; *(uint4*)&B0[wofsB + 64 * 32] = rb1;
;   }
;   ra0 = *(const uint4*)(pa0 + 32); ra1 = *(const uint4*)(pa1 + 32); ra2 = *(const uint4*)(pa2 + 32); ra3 = *(const uint4*)(pa3 + 32);
;   rb0 = *(const uint4*)(pb0 + 32); rb1 = *(const uint4*)(pb1 + 32);
;   __syncthreads();
;   const int rsw = (fq ^ ((fr >> 2) & 3)) * 8;
;   const int rdA = (wr * 128 + fr) * 32 + rsw, rdB = 256 * 32 + (wc * 64 + fr) * 32 + rsw;
; __device__ __forceinline__ void moe_up_tile(const Params& p, char* smem, int l, int e, int nt, int b, int mt, bool isctx) {
;     ...
;   auto rowA = [&](int r) {
;     int row;
;     if (isctx) { int s_ = r < 64 ? r : 0; int bb = s_ >> 5; row = MLAT + bb * 256 + idxC[(bb * 16 + e) * 32 + (s_ & 31)]; }
;     else row = b * 8192 + idxL[r];
;     return H2 + (size_t)row * 1024;
;   };
;   auto rowB = [&](int r) { return W + (size_t)(nt * 128 + r) * 1024; };
.LBB0_1659:
	s_lshl_b32 s11, s18, 8
	s_add_u32 s0, s4, 0x1d3d6100
	s_addc_u32 s1, s5, 0
	s_lshl_b32 s6, s17, 4
	s_add_i32 s6, s6, s13
	s_ashr_i32 s7, s6, 31
	s_and_b32 s10, s16, 31
	s_lshl_b64 s[6:7], s[6:7], 23
	v_ashrrev_i32_e32 v5, 31, v4
	s_add_u32 s8, s4, s6
	v_ashrrev_i32_e32 v9, 31, v8
	v_lshlrev_b32_e32 v0, 4, v192
	v_ashrrev_i32_e32 v7, 31, v6
	v_lshlrev_b64 v[36:37], 11, v[4:5]
	s_addc_u32 s9, s5, s7
	v_ashrrev_i32_e32 v11, 31, v10
	s_waitcnt vmcnt(0)
	v_lshlrev_b64 v[28:29], 11, v[8:9]
	v_and_b32_e32 v0, 48, v0
	v_lshlrev_b64 v[32:33], 11, v[6:7]
	v_lshl_add_u64 v[4:5], s[0:1], 0, v[36:37]
	s_add_u32 s8, s8, 0xe00000
	v_lshlrev_b64 v[40:41], 11, v[10:11]
	v_lshl_add_u64 v[8:9], s[0:1], 0, v[28:29]
	v_lshl_add_u64 v[6:7], s[0:1], 0, v[32:33]
	v_lshl_add_u64 v[38:39], v[4:5], 0, v[0:1]
	s_addc_u32 s9, s9, 0
	v_lshl_add_u64 v[4:5], s[0:1], 0, v[40:41]
	s_lshl_b32 s0, s10, 7
	v_lshl_add_u64 v[30:31], v[8:9], 0, v[0:1]
	v_lshl_add_u64 v[34:35], v[6:7], 0, v[0:1]
	v_add_u32_e32 v6, s0, v2
	v_add_u32_e32 v8, s0, v12
	v_ashrrev_i32_e32 v7, 31, v6
	v_ashrrev_i32_e32 v9, 31, v8
	v_lshlrev_b64 v[42:43], 11, v[6:7]
	v_lshlrev_b64 v[44:45], 11, v[8:9]
	v_lshl_add_u64 v[6:7], s[8:9], 0, v[42:43]
	v_lshl_add_u64 v[8:9], s[8:9], 0, v[44:45]
	v_lshl_add_u64 v[46:47], v[4:5], 0, v[0:1]
	v_lshl_add_u64 v[48:49], v[6:7], 0, v[0:1]
	v_lshl_add_u64 v[50:51], v[8:9], 0, v[0:1]
	global_load_dwordx4 v[4:7], v[38:39], off
	global_load_dwordx4 v[8:11], v[34:35], off
	global_load_dwordx4 v[12:15], v[30:31], off
	global_load_dwordx4 v[16:19], v[46:47], off
	global_load_dwordx4 v[20:23], v[48:49], off
	global_load_dwordx4 v[24:27], v[50:51], off
	v_lshrrev_b32_e32 v193, 4, v192
	v_xor_b32_e32 v3, v193, v192
	v_lshlrev_b32_e32 v2, 5, v2
	v_lshlrev_b32_e32 v3, 3, v3
	v_and_or_b32 v215, v3, 24, v2
	v_lshlrev_b32_e32 v214, 1, v215
	s_waitcnt lgkmcnt(0)
	s_barrier
	v_lshrrev_b32_e32 v3, 2, v192
	v_and_b32_e32 v179, 0xffffff80, v192
	v_xor_b32_e32 v3, v193, v3
	v_sub_u32_e32 v2, s14, v179
	v_lshlrev_b32_e32 v3, 3, v3
	v_ashrrev_i32_e32 v2, 4, v2
	v_and_b32_e32 v216, 24, v3
	v_lshlrev_b32_e32 v3, 5, v192
	s_movk_i32 s0, 0xf1e0
	v_and_or_b32 v213, v3, s0, v216
	v_cmp_lt_i32_e64 s[0:1], 0, v2
	v_cmp_lt_i32_e32 vcc, 4, v2
	s_add_u32 s8, s4, 0xe00080
	v_lshl_add_u64 v[2:3], s[6:7], 0, v[44:45]
	s_addc_u32 s9, s5, 0
	v_or_b32_e32 v2, v2, v0
	v_lshl_add_u64 v[180:181], s[8:9], 0, v[2:3]
	v_lshl_add_u64 v[2:3], s[6:7], 0, v[42:43]
	v_or_b32_e32 v2, v2, v0
	s_add_u32 s6, s4, 0x1d3d6180
	v_lshl_add_u64 v[182:183], s[8:9], 0, v[2:3]
	s_addc_u32 s7, s5, 0
	v_or_b32_e32 v40, v40, v0
	v_or_b32_e32 v28, v28, v0
	v_or_b32_e32 v32, v32, v0
	v_or_b32_e32 v36, v36, v0
	v_mov_b32_e32 v2, v1
	v_mov_b32_e32 v3, v1
	v_bfe_u32 v211, v192, 6, 1
	v_and_b32_e32 v212, 15, v192
	v_lshl_add_u64 v[184:185], s[6:7], 0, v[40:41]
	v_lshl_add_u64 v[186:187], s[6:7], 0, v[28:29]
	v_lshl_add_u64 v[188:189], s[6:7], 0, v[32:33]
	v_lshl_add_u64 v[190:191], s[6:7], 0, v[36:37]
	v_mov_b32_e32 v0, v1
	v_mov_b64_e32 v[42:43], v[2:3]
	v_mov_b64_e32 v[54:55], v[2:3]
	v_mov_b64_e32 v[62:63], v[2:3]
	v_mov_b64_e32 v[58:59], v[2:3]
	v_mov_b64_e32 v[66:67], v[2:3]
	v_mov_b64_e32 v[70:71], v[2:3]
	v_mov_b64_e32 v[78:79], v[2:3]
	v_mov_b64_e32 v[74:75], v[2:3]
	s_waitcnt vmcnt(0)
	ds_write_b128 v214, v[4:7]
	ds_write_b128 v214, v[8:11] offset:4096
	ds_write_b128 v214, v[12:15] offset:8192
	ds_write_b128 v214, v[16:19] offset:12288
	ds_write_b128 v214, v[20:23] offset:16384
	ds_write_b128 v214, v[24:27] offset:20480
	global_load_dwordx4 v[132:135], v[34:35], off offset:64
	global_load_dwordx4 v[140:143], v[30:31], off offset:64
	global_load_dwordx4 v[136:139], v[38:39], off offset:64
	global_load_dwordx4 v[144:147], v[46:47], off offset:64
	global_load_dwordx4 v[148:151], v[48:49], off offset:64
	global_load_dwordx4 v[152:155], v[50:51], off offset:64
	v_mov_b64_e32 v[6:7], v[2:3]
	v_mov_b64_e32 v[14:15], v[2:3]
	v_mov_b64_e32 v[10:11], v[2:3]
	v_mov_b64_e32 v[18:19], v[2:3]
	v_mov_b64_e32 v[22:23], v[2:3]
	v_mov_b64_e32 v[30:31], v[2:3]
	v_mov_b64_e32 v[26:27], v[2:3]
	v_mov_b64_e32 v[34:35], v[2:3]
	v_mov_b64_e32 v[38:39], v[2:3]
	v_mov_b64_e32 v[46:47], v[2:3]
	v_mov_b64_e32 v[50:51], v[2:3]
	v_mov_b64_e32 v[82:83], v[2:3]
	v_mov_b64_e32 v[86:87], v[2:3]
	v_mov_b64_e32 v[94:95], v[2:3]
	v_mov_b64_e32 v[90:91], v[2:3]
	v_mov_b64_e32 v[98:99], v[2:3]
	v_mov_b64_e32 v[102:103], v[2:3]
	v_mov_b64_e32 v[110:111], v[2:3]
	v_mov_b64_e32 v[106:107], v[2:3]
	v_mov_b64_e32 v[114:115], v[2:3]
	v_mov_b64_e32 v[118:119], v[2:3]
	v_mov_b64_e32 v[126:127], v[2:3]
	v_mov_b64_e32 v[122:123], v[2:3]
	v_mov_b64_e32 v[130:131], v[2:3]
	s_mov_b32 s16, 1
	v_lshlrev_b32_e32 v217, 12, v211
	v_lshlrev_b32_e32 v218, 6, v212
	s_mov_b64 s[6:7], 0
	v_mov_b64_e32 v[4:5], v[0:1]
	v_mov_b64_e32 v[12:13], v[0:1]
	v_mov_b64_e32 v[8:9], v[0:1]
	v_mov_b64_e32 v[16:17], v[0:1]
	v_mov_b64_e32 v[20:21], v[0:1]
	v_mov_b64_e32 v[28:29], v[0:1]
	v_mov_b64_e32 v[24:25], v[0:1]
	v_mov_b64_e32 v[32:33], v[0:1]
	v_mov_b64_e32 v[36:37], v[0:1]
	v_mov_b64_e32 v[44:45], v[0:1]
	v_mov_b64_e32 v[40:41], v[0:1]
	v_mov_b64_e32 v[48:49], v[0:1]
	v_mov_b64_e32 v[52:53], v[0:1]
	v_mov_b64_e32 v[60:61], v[0:1]
	v_mov_b64_e32 v[56:57], v[0:1]
	v_mov_b64_e32 v[64:65], v[0:1]
	v_mov_b64_e32 v[68:69], v[0:1]
	v_mov_b64_e32 v[76:77], v[0:1]
	v_mov_b64_e32 v[72:73], v[0:1]
	v_mov_b64_e32 v[80:81], v[0:1]
	v_mov_b64_e32 v[84:85], v[0:1]
	v_mov_b64_e32 v[92:93], v[0:1]
	v_mov_b64_e32 v[88:89], v[0:1]
	v_mov_b64_e32 v[96:97], v[0:1]
	v_mov_b64_e32 v[100:101], v[0:1]
	v_mov_b64_e32 v[108:109], v[0:1]
	v_mov_b64_e32 v[104:105], v[0:1]
	v_mov_b64_e32 v[112:113], v[0:1]
	v_mov_b64_e32 v[116:117], v[0:1]
	v_mov_b64_e32 v[124:125], v[0:1]
	v_mov_b64_e32 v[120:121], v[0:1]
	v_mov_b64_e32 v[128:129], v[0:1]
	s_waitcnt lgkmcnt(0)
	s_barrier
	s_and_b64 s[8:9], s[0:1], vcc
	s_cmp_eq_u64 s[8:9], exec
	s_cbranch_scc1 .Lp6_fk
	s_branch .LBB0_1661
; template <int K, class FA, class FB, class Epi>
; __device__ __forceinline__ void gemm_tile(char* smem, int nvalid_rows, FA rowA, FB rowB, Epi epi) {
;     ...
;   for (int kt = 0; kt < NK; ++kt) {
;     const u16* Bc = (const u16*)(smem + (kt & 1) * 24576);
;     bf16x8 Bt[4];
; #pragma unroll
;     for (int n = 0; n < 4; ++n) Bt[n] = *(const bf16x8*)&Bc[rdB + n * 16 * 32];
;     if (msub > 0) {
;       bf16x8 At[4];
; #pragma unroll
;       for (int m = 0; m < 4; ++m) At[m] = *(const bf16x8*)&Bc[rdA + m * 16 * 32];
;       __builtin_amdgcn_s_setprio(1);
; #pragma unroll
;       for (int m = 0; m < 4; ++m)
; #pragma unroll
;         for (int n = 0; n < 4; ++n) acc[m][n] = __builtin_amdgcn_mfma_f32_16x16x32_bf16(At[m], Bt[n], acc[m][n], 0, 0, 0);
;       __builtin_amdgcn_s_setprio(0);
;     }
;     if (msub > 4) {
;       bf16x8 At[4];
; #pragma unroll
;       for (int m = 0; m < 4; ++m) At[m] = *(const bf16x8*)&Bc[rdA + (m + 4) * 16 * 32];
;       __builtin_amdgcn_s_setprio(1);
; #pragma unroll
;       for (int m = 0; m < 4; ++m)
; #pragma unroll
;         for (int n = 0; n < 4; ++n) acc[m + 4][n] = __builtin_amdgcn_mfma_f32_16x16x32_bf16(At[m], Bt[n], acc[m + 4][n], 0, 0, 0);
;       __builtin_amdgcn_s_setprio(0);
;     }
;     if (kt + 1 < NK) {
;       u16* Bn = (u16*)(smem + ((kt + 1) & 1) * 24576);
;       *(uint4*)&Bn[wofsA] = ra0; *(uint4*)&Bn[wofsA + 64 * 32] = ra1;
;       *(uint4*)&Bn[wofsA + 128 * 32] = ra2; *(uint4*)&Bn[wofsA + 192 * 32] = ra3;
;       *(uint4*)&Bn[wofsB] = rb0; *(uint4*)&Bn[wofsB + 64 * 32] = rb1;
;     }
;     if (kt + 2 < NK) {
;       const int ko = (kt + 2) * 32;
;       ra0 = *(const uint4*)(pa0 + ko); ra1 = *(const uint4*)(pa1 + ko); ra2 = *(const uint4*)(pa2 + ko); ra3 = *(const uint4*)(pa3 + ko);
;       rb0 = *(const uint4*)(pb0 + ko); rb1 = *(const uint4*)(pb1 + ko);
;     }
;     __syncthreads();
;   }
.Lp6_fk:
	s_and_b32 s17, 1, s16
	s_cselect_b32 s18, 0, 0x6000
	v_or_b32_e32 v2, s18, v217
	v_lshlrev_b32_e32 v0, 1, v216
	v_add3_u32 v2, v2, v218, v0
	ds_read_b128 v[156:159], v2 offset:16384
	ds_read_b128 v[160:163], v2 offset:17408
	ds_read_b128 v[164:167], v2 offset:18432
	ds_read_b128 v[168:171], v2 offset:19456
	v_lshl_add_u32 v2, v213, 1, s18
	ds_read_b128 v[220:223], v2
	ds_read_b128 v[224:227], v2 offset:1024
	ds_read_b128 v[228:231], v2 offset:2048
	ds_read_b128 v[232:235], v2 offset:3072
	s_setprio 1
	s_waitcnt lgkmcnt(0)
	v_mfma_f32_16x16x32_bf16 v[128:131], v[220:223], v[156:159], v[128:131]
	v_mfma_f32_16x16x32_bf16 v[120:123], v[220:223], v[160:163], v[120:123]
	v_mfma_f32_16x16x32_bf16 v[124:127], v[220:223], v[164:167], v[124:127]
	v_mfma_f32_16x16x32_bf16 v[116:119], v[220:223], v[168:171], v[116:119]
	v_mfma_f32_16x16x32_bf16 v[112:115], v[224:227], v[156:159], v[112:115]
	v_mfma_f32_16x16x32_bf16 v[104:107], v[224:227], v[160:163], v[104:107]
	v_mfma_f32_16x16x32_bf16 v[108:111], v[224:227], v[164:167], v[108:111]
	v_mfma_f32_16x16x32_bf16 v[100:103], v[224:227], v[168:171], v[100:103]
	v_mfma_f32_16x16x32_bf16 v[96:99], v[228:231], v[156:159], v[96:99]
	v_mfma_f32_16x16x32_bf16 v[88:91], v[228:231], v[160:163], v[88:91]
	v_mfma_f32_16x16x32_bf16 v[92:95], v[228:231], v[164:167], v[92:95]
	v_mfma_f32_16x16x32_bf16 v[84:87], v[228:231], v[168:171], v[84:87]
	v_mfma_f32_16x16x32_bf16 v[80:83], v[232:235], v[156:159], v[80:83]
	v_mfma_f32_16x16x32_bf16 v[72:75], v[232:235], v[160:163], v[72:75]
	v_mfma_f32_16x16x32_bf16 v[76:79], v[232:235], v[164:167], v[76:79]
	v_mfma_f32_16x16x32_bf16 v[68:71], v[232:235], v[168:171], v[68:71]
	s_setprio 0
	v_lshl_add_u32 v2, v213, 1, s18
	ds_read_b128 v[220:223], v2 offset:4096
	ds_read_b128 v[224:227], v2 offset:5120
	ds_read_b128 v[228:231], v2 offset:6144
	ds_read_b128 v[232:235], v2 offset:7168
	s_setprio 1
	s_waitcnt lgkmcnt(0)
	v_mfma_f32_16x16x32_bf16 v[64:67], v[220:223], v[156:159], v[64:67]
	v_mfma_f32_16x16x32_bf16 v[56:59], v[220:223], v[160:163], v[56:59]
	v_mfma_f32_16x16x32_bf16 v[60:63], v[220:223], v[164:167], v[60:63]
	v_mfma_f32_16x16x32_bf16 v[52:55], v[220:223], v[168:171], v[52:55]
	v_mfma_f32_16x16x32_bf16 v[48:51], v[224:227], v[156:159], v[48:51]
	v_mfma_f32_16x16x32_bf16 v[40:43], v[224:227], v[160:163], v[40:43]
	v_mfma_f32_16x16x32_bf16 v[44:47], v[224:227], v[164:167], v[44:47]
	v_mfma_f32_16x16x32_bf16 v[36:39], v[224:227], v[168:171], v[36:39]
	v_mfma_f32_16x16x32_bf16 v[32:35], v[228:231], v[156:159], v[32:35]
	v_mfma_f32_16x16x32_bf16 v[24:27], v[228:231], v[160:163], v[24:27]
	v_mfma_f32_16x16x32_bf16 v[28:31], v[228:231], v[164:167], v[28:31]
	v_mfma_f32_16x16x32_bf16 v[20:23], v[228:231], v[168:171], v[20:23]
	v_mfma_f32_16x16x32_bf16 v[16:19], v[232:235], v[156:159], v[16:19]
	v_mfma_f32_16x16x32_bf16 v[8:11], v[232:235], v[160:163], v[8:11]
	v_mfma_f32_16x16x32_bf16 v[12:15], v[232:235], v[164:167], v[12:15]
	v_mfma_f32_16x16x32_bf16 v[4:7], v[232:235], v[168:171], v[4:7]
	s_setprio 0
	s_cmp_eq_u32 s17, 1
	s_cselect_b32 s8, 0x6000, 0
	v_lshl_add_u32 v2, v215, 1, s8
	s_waitcnt vmcnt(0)
	ds_write_b128 v2, v[136:139]
	ds_write_b128 v2, v[132:135] offset:4096
	ds_write_b128 v2, v[140:143] offset:8192
	ds_write_b128 v2, v[144:147] offset:12288
	ds_write_b128 v2, v[148:151] offset:16384
	ds_write_b128 v2, v[152:155] offset:20480
	v_lshl_add_u64 v[2:3], v[190:191], 0, s[6:7]
	v_lshl_add_u64 v[132:133], v[188:189], 0, s[6:7]
	global_load_dwordx4 v[136:139], v[2:3], off
	s_nop 0
	global_load_dwordx4 v[132:135], v[132:133], off
	v_lshl_add_u64 v[2:3], v[186:187], 0, s[6:7]
	v_lshl_add_u64 v[144:145], v[184:185], 0, s[6:7]
	global_load_dwordx4 v[140:143], v[2:3], off
	s_nop 0
	global_load_dwordx4 v[144:147], v[144:145], off
	v_lshl_add_u64 v[2:3], v[182:183], 0, s[6:7]
	v_lshl_add_u64 v[152:153], v[180:181], 0, s[6:7]
	global_load_dwordx4 v[148:151], v[2:3], off
	s_nop 0
	global_load_dwordx4 v[152:155], v[152:153], off
	s_add_u32 s6, s6, 64
	s_addc_u32 s7, s7, 0
	s_add_i32 s16, s16, 1
	s_cmpk_eq_i32 s6, 0x780
	s_waitcnt lgkmcnt(0)
	s_barrier
	s_cbranch_scc0 .Lp6_fk
	s_branch .LBB0_1665

; template <int K, class FA, class FB, class Epi>
; __device__ __forceinline__ void gemm_tile(char* smem, int nvalid_rows, FA rowA, FB rowB, Epi epi) {
;   const int tid = vtid(), lane = tid & 63, wid = tid >> 6, wr = wid >> 1, wc = wid & 1, fr = lane & 15, fq = lane >> 4;
;   const int seg = tid & 3, r0 = tid >> 2;
;   int msub = (nvalid_rows - wr * 128 + 15) >> 4;
;   msub = msub < 0 ? 0 : (msub > 8 ? 8 : msub);
;   const u16* pa0 = rowA(r0) + seg * 8;
;   const u16* pa1 = rowA(r0 + 64) + seg * 8;
;   const u16* pa2 = rowA(r0 + 128) + seg * 8;
;   const u16* pa3 = rowA(r0 + 192) + seg * 8;
;   const u16* pb0 = rowB(r0) + seg * 8;
;   const u16* pb1 = rowB(r0 + 64) + seg * 8;
;   f32x4 acc[8][4];
; #pragma unroll
;   for (int m = 0; m < 8; ++m)
; #pragma unroll
;     for (int n = 0; n < 4; ++n) acc[m][n] = (f32x4){0.f, 0.f, 0.f, 0.f};
;   uint4 ra0, ra1, ra2, ra3, rb0, rb1;
;   ra0 = *(const uint4*)pa0; ra1 = *(const uint4*)pa1; ra2 = *(const uint4*)pa2; ra3 = *(const uint4*)pa3;
;   rb0 = *(const uint4*)pb0; rb1 = *(const uint4*)pb1;
;   constexpr int NK = K / 32;
;   const int wsw = (seg ^ ((r0 >> 2) & 3)) * 8;
;   const int wofsA = r0 * 32 + wsw, wofsB = 256 * 32 + r0 * 32 + wsw;
;   __syncthreads();
;   {
;     u16* B0 = (u16*)smem;
;     *(uint4*)&B0[wofsA] = ra0; *(uint4*)&B0[wofsA + 64 * 32] = ra1;
;     *(uint4*)&B0[wofsA + 128 * 32] = ra2; *(uint4*)&B0[wofsA + 192 * 32] = ra3;
;     *(uint4*)&B0[wofsB] = rb0; *(uint4*)&B0[wofsB + 64 * 32] = rb1;
;   }
;   ra0 = *(const uint4*)(pa0 + 32); ra1 = *(const uint4*)(pa1 + 32); ra2 = *(const uint4*)(pa2 + 32); ra3 = *(const uint4*)(pa3 + 32);
;   rb0 = *(const uint4*)(pb0 + 32); rb1 = *(const uint4*)(pb1 + 32);
;   __syncthreads();
;   const int rsw = (fq ^ ((fr >> 2) & 3)) * 8;
;   const int rdA = (wr * 128 + fr) * 32 + rsw, rdB = 256 * 32 + (wc * 64 + fr) * 32 + rsw;
; __device__ __forceinline__ void moe_down_tile(const Params& p, char* smem, int l, int e, int nt, int b, int mt, bool isctx, int ks) {
;     ...
;   const int koff = ks < 0 ? 0 : ks * 512;
;   auto rowA = [&](int r) {
;     if (isctx) { int s_ = r < 64 ? r : 0; return ACTC + ((size_t)(((s_ >> 5) * 16 + e) * 32 + (s_ & 31))) * 2048 + koff; }
;     return ACTL + (size_t)r * 2048;
;   };
;   auto rowB = [&](int r) { return W + (size_t)(nt * 128 + r) * 2048 + koff; };
.LBB0_1807:
	s_lshl_b32 s6, s35, 7
	v_add_u32_e32 v18, s6, v4
	v_add_u32_e32 v10, s6, v10
	v_ashrrev_i32_e32 v19, 31, v18
	v_ashrrev_i32_e32 v11, 31, v10
	v_lshlrev_b32_e32 v0, 4, v16
	v_lshlrev_b64 v[46:47], 12, v[18:19]
	v_lshlrev_b64 v[10:11], 12, v[10:11]
	v_and_b32_e32 v0, 48, v0
	v_lshl_add_u64 v[18:19], s[16:17], 0, v[46:47]
	s_lshl_b32 s2, s20, 1
	v_lshl_add_u64 v[20:21], s[16:17], 0, v[10:11]
	v_lshl_add_u64 v[44:45], v[2:3], 0, v[0:1]
	v_lshl_add_u64 v[18:19], v[18:19], 0, s[2:3]
	v_lshl_add_u64 v[20:21], v[20:21], 0, s[2:3]
	v_lshl_add_u64 v[14:15], v[8:9], 0, v[0:1]
	v_lshl_add_u64 v[42:43], v[6:7], 0, v[0:1]
	v_lshl_add_u64 v[48:49], v[12:13], 0, v[0:1]
	v_lshl_add_u64 v[50:51], v[18:19], 0, v[0:1]
	v_lshl_add_u64 v[52:53], v[20:21], 0, v[0:1]
	global_load_dwordx4 v[18:21], v[44:45], off
	global_load_dwordx4 v[22:25], v[42:43], off
	global_load_dwordx4 v[26:29], v[14:15], off
	global_load_dwordx4 v[30:33], v[48:49], off
	global_load_dwordx4 v[34:37], v[50:51], off
	global_load_dwordx4 v[38:41], v[52:53], off
	v_lshrrev_b32_e32 v179, 4, v16
	v_lshlrev_b32_e32 v0, 5, v4
	v_xor_b32_e32 v4, v179, v16
	v_lshlrev_b32_e32 v4, 3, v4
	v_and_or_b32 v213, v4, 24, v0
	v_lshlrev_b32_e32 v212, 1, v213
	s_waitcnt lgkmcnt(0)
	s_barrier
	v_lshrrev_b32_e32 v4, 2, v16
	v_and_b32_e32 v181, 0xffffff80, v16
	v_xor_b32_e32 v4, v179, v4
	v_sub_u32_e32 v0, s28, v181
	v_lshlrev_b32_e32 v4, 3, v4
	v_ashrrev_i32_e32 v0, 4, v0
	v_and_b32_e32 v215, 24, v4
	v_lshlrev_b32_e32 v4, 5, v16
	s_movk_i32 s0, 0xf1e0
	s_add_u32 s2, s10, s2
	v_and_or_b32 v214, v4, s0, v215
	v_cmp_lt_i32_e64 s[0:1], 0, v0
	v_cmp_lt_i32_e32 vcc, 4, v0
	v_and_b32_e32 v0, 3, v16
	s_addc_u32 s21, s11, 0
	v_lshl_add_u64 v[4:5], s[12:13], 0, v[10:11]
	v_lshlrev_b32_e32 v0, 4, v0
	s_add_u32 s20, s2, 0x10e00080
	v_lshl_add_u64 v[4:5], v[4:5], 0, v[0:1]
	s_addc_u32 s21, s21, 0
	v_lshl_add_u64 v[182:183], s[20:21], 0, v[4:5]
	v_lshl_add_u64 v[4:5], s[12:13], 0, v[46:47]
	v_lshl_add_u64 v[4:5], v[4:5], 0, v[0:1]
	v_lshl_add_u64 v[184:185], s[20:21], 0, v[4:5]
	v_lshl_add_u64 v[4:5], v[12:13], 0, v[0:1]
	s_mov_b64 s[20:21], 0x80
	v_lshl_add_u64 v[186:187], v[4:5], 0, s[20:21]
	v_lshl_add_u64 v[4:5], v[8:9], 0, v[0:1]
	v_lshl_add_u64 v[2:3], v[2:3], 0, v[0:1]
	v_lshl_add_u64 v[188:189], v[4:5], 0, s[20:21]
	v_lshl_add_u64 v[4:5], v[6:7], 0, v[0:1]
	v_lshl_add_u64 v[192:193], v[2:3], 0, s[20:21]
	v_mov_b32_e32 v2, v1
	v_mov_b32_e32 v3, v1
	v_bfe_u32 v211, v16, 6, 1
	v_and_b32_e32 v180, 15, v16
	v_lshl_add_u64 v[190:191], v[4:5], 0, s[20:21]
	v_mov_b32_e32 v0, v1
	v_mov_b64_e32 v[6:7], v[2:3]
	v_mov_b64_e32 v[10:11], v[2:3]
	v_mov_b64_e32 v[58:59], v[2:3]
	v_mov_b64_e32 v[62:63], v[2:3]
	v_mov_b64_e32 v[66:67], v[2:3]
	v_mov_b64_e32 v[70:71], v[2:3]
	v_mov_b64_e32 v[74:75], v[2:3]
	v_mov_b64_e32 v[78:79], v[2:3]
	v_mov_b64_e32 v[82:83], v[2:3]
	v_mov_b64_e32 v[86:87], v[2:3]
	v_mov_b64_e32 v[90:91], v[2:3]
	v_mov_b64_e32 v[94:95], v[2:3]
	v_mov_b64_e32 v[98:99], v[2:3]
	v_mov_b64_e32 v[102:103], v[2:3]
	v_mov_b64_e32 v[106:107], v[2:3]
	v_mov_b64_e32 v[110:111], v[2:3]
	v_mov_b64_e32 v[114:115], v[2:3]
	v_mov_b64_e32 v[118:119], v[2:3]
	s_waitcnt vmcnt(0)
	ds_write_b128 v212, v[18:21]
	ds_write_b128 v212, v[22:25] offset:4096
	ds_write_b128 v212, v[26:29] offset:8192
	ds_write_b128 v212, v[30:33] offset:12288
	ds_write_b128 v212, v[34:37] offset:16384
	ds_write_b128 v212, v[38:41] offset:20480
	global_load_dwordx4 v[132:135], v[44:45], off offset:64
	global_load_dwordx4 v[136:139], v[42:43], off offset:64
	global_load_dwordx4 v[140:143], v[14:15], off offset:64
	global_load_dwordx4 v[144:147], v[48:49], off offset:64
	global_load_dwordx4 v[148:151], v[50:51], off offset:64
	global_load_dwordx4 v[152:155], v[52:53], off offset:64
	v_mov_b64_e32 v[14:15], v[2:3]
	v_mov_b64_e32 v[18:19], v[2:3]
	v_mov_b64_e32 v[22:23], v[2:3]
	v_mov_b64_e32 v[26:27], v[2:3]
	v_mov_b64_e32 v[30:31], v[2:3]
	v_mov_b64_e32 v[34:35], v[2:3]
	v_mov_b64_e32 v[38:39], v[2:3]
	v_mov_b64_e32 v[42:43], v[2:3]
	v_mov_b64_e32 v[46:47], v[2:3]
	v_mov_b64_e32 v[50:51], v[2:3]
	v_mov_b64_e32 v[54:55], v[2:3]
	v_mov_b64_e32 v[122:123], v[2:3]
	v_mov_b64_e32 v[126:127], v[2:3]
	v_mov_b64_e32 v[130:131], v[2:3]
	s_mov_b32 s7, 1
	v_lshlrev_b32_e32 v216, 12, v211
	v_lshlrev_b32_e32 v217, 6, v180
	s_mov_b64 s[20:21], 0
	v_mov_b64_e32 v[4:5], v[0:1]
	v_mov_b64_e32 v[8:9], v[0:1]
	v_mov_b64_e32 v[12:13], v[0:1]
	v_mov_b64_e32 v[16:17], v[0:1]
	v_mov_b64_e32 v[20:21], v[0:1]
	v_mov_b64_e32 v[24:25], v[0:1]
	v_mov_b64_e32 v[28:29], v[0:1]
	v_mov_b64_e32 v[32:33], v[0:1]
	v_mov_b64_e32 v[36:37], v[0:1]
	v_mov_b64_e32 v[40:41], v[0:1]
	v_mov_b64_e32 v[44:45], v[0:1]
	v_mov_b64_e32 v[48:49], v[0:1]
	v_mov_b64_e32 v[52:53], v[0:1]
	v_mov_b64_e32 v[56:57], v[0:1]
	v_mov_b64_e32 v[60:61], v[0:1]
	v_mov_b64_e32 v[64:65], v[0:1]
	v_mov_b64_e32 v[68:69], v[0:1]
	v_mov_b64_e32 v[72:73], v[0:1]
	v_mov_b64_e32 v[76:77], v[0:1]
	v_mov_b64_e32 v[80:81], v[0:1]
	v_mov_b64_e32 v[84:85], v[0:1]
	v_mov_b64_e32 v[88:89], v[0:1]
	v_mov_b64_e32 v[92:93], v[0:1]
	v_mov_b64_e32 v[96:97], v[0:1]
	v_mov_b64_e32 v[100:101], v[0:1]
	v_mov_b64_e32 v[104:105], v[0:1]
	v_mov_b64_e32 v[108:109], v[0:1]
	v_mov_b64_e32 v[112:113], v[0:1]
	v_mov_b64_e32 v[116:117], v[0:1]
	v_mov_b64_e32 v[120:121], v[0:1]
	v_mov_b64_e32 v[124:125], v[0:1]
	v_mov_b64_e32 v[128:129], v[0:1]
	s_waitcnt lgkmcnt(0)
	s_barrier
	s_and_b64 s[22:23], s[0:1], vcc
	s_cmp_eq_u64 s[22:23], exec
	s_cbranch_scc1 .Lp7a_fk
	s_branch .LBB0_1809
; template <int K, class FA, class FB, class Epi>
; __device__ __forceinline__ void gemm_tile(char* smem, int nvalid_rows, FA rowA, FB rowB, Epi epi) {
;     ...
;   for (int kt = 0; kt < NK; ++kt) {
;     const u16* Bc = (const u16*)(smem + (kt & 1) * 24576);
;     bf16x8 Bt[4];
; #pragma unroll
;     for (int n = 0; n < 4; ++n) Bt[n] = *(const bf16x8*)&Bc[rdB + n * 16 * 32];
;     if (msub > 0) {
;       bf16x8 At[4];
; #pragma unroll
;       for (int m = 0; m < 4; ++m) At[m] = *(const bf16x8*)&Bc[rdA + m * 16 * 32];
;       __builtin_amdgcn_s_setprio(1);
; #pragma unroll
;       for (int m = 0; m < 4; ++m)
; #pragma unroll
;         for (int n = 0; n < 4; ++n) acc[m][n] = __builtin_amdgcn_mfma_f32_16x16x32_bf16(At[m], Bt[n], acc[m][n], 0, 0, 0);
;       __builtin_amdgcn_s_setprio(0);
;     }
;     if (msub > 4) {
;       bf16x8 At[4];
; #pragma unroll
;       for (int m = 0; m < 4; ++m) At[m] = *(const bf16x8*)&Bc[rdA + (m + 4) * 16 * 32];
;       __builtin_amdgcn_s_setprio(1);
; #pragma unroll
;       for (int m = 0; m < 4; ++m)
; #pragma unroll
;         for (int n = 0; n < 4; ++n) acc[m + 4][n] = __builtin_amdgcn_mfma_f32_16x16x32_bf16(At[m], Bt[n], acc[m + 4][n], 0, 0, 0);
;       __builtin_amdgcn_s_setprio(0);
;     }
;     if (kt + 1 < NK) {
;       u16* Bn = (u16*)(smem + ((kt + 1) & 1) * 24576);
;       *(uint4*)&Bn[wofsA] = ra0; *(uint4*)&Bn[wofsA + 64 * 32] = ra1;
;       *(uint4*)&Bn[wofsA + 128 * 32] = ra2; *(uint4*)&Bn[wofsA + 192 * 32] = ra3;
;       *(uint4*)&Bn[wofsB] = rb0; *(uint4*)&Bn[wofsB + 64 * 32] = rb1;
;     }
;     if (kt + 2 < NK) {
;       const int ko = (kt + 2) * 32;
;       ra0 = *(const uint4*)(pa0 + ko); ra1 = *(const uint4*)(pa1 + ko); ra2 = *(const uint4*)(pa2 + ko); ra3 = *(const uint4*)(pa3 + ko);
;       rb0 = *(const uint4*)(pb0 + ko); rb1 = *(const uint4*)(pb1 + ko);
;     }
;     __syncthreads();
;   }
.Lp7a_fk:
	s_and_b32 s2, 1, s7
	s_cselect_b32 s24, 0, 0x6000
	v_or_b32_e32 v2, s24, v216
	v_lshlrev_b32_e32 v0, 1, v215
	v_add3_u32 v2, v2, v217, v0
	ds_read_b128 v[156:159], v2 offset:16384
	ds_read_b128 v[160:163], v2 offset:17408
	ds_read_b128 v[164:167], v2 offset:18432
	ds_read_b128 v[168:171], v2 offset:19456
	v_lshl_add_u32 v2, v214, 1, s24
	ds_read_b128 v[218:221], v2
	ds_read_b128 v[222:225], v2 offset:1024
	ds_read_b128 v[226:229], v2 offset:2048
	ds_read_b128 v[230:233], v2 offset:3072
	s_setprio 1
	s_waitcnt lgkmcnt(0)
	v_mfma_f32_16x16x32_bf16 v[128:131], v[218:221], v[156:159], v[128:131]
	v_mfma_f32_16x16x32_bf16 v[124:127], v[218:221], v[160:163], v[124:127]
	v_mfma_f32_16x16x32_bf16 v[120:123], v[218:221], v[164:167], v[120:123]
	v_mfma_f32_16x16x32_bf16 v[116:119], v[218:221], v[168:171], v[116:119]
	v_mfma_f32_16x16x32_bf16 v[112:115], v[222:225], v[156:159], v[112:115]
	v_mfma_f32_16x16x32_bf16 v[108:111], v[222:225], v[160:163], v[108:111]
	v_mfma_f32_16x16x32_bf16 v[104:107], v[222:225], v[164:167], v[104:107]
	v_mfma_f32_16x16x32_bf16 v[100:103], v[222:225], v[168:171], v[100:103]
	v_mfma_f32_16x16x32_bf16 v[96:99], v[226:229], v[156:159], v[96:99]
	v_mfma_f32_16x16x32_bf16 v[92:95], v[226:229], v[160:163], v[92:95]
	v_mfma_f32_16x16x32_bf16 v[88:91], v[226:229], v[164:167], v[88:91]
	v_mfma_f32_16x16x32_bf16 v[84:87], v[226:229], v[168:171], v[84:87]
	v_mfma_f32_16x16x32_bf16 v[80:83], v[230:233], v[156:159], v[80:83]
	v_mfma_f32_16x16x32_bf16 v[76:79], v[230:233], v[160:163], v[76:79]
	v_mfma_f32_16x16x32_bf16 v[72:75], v[230:233], v[164:167], v[72:75]
	v_mfma_f32_16x16x32_bf16 v[68:71], v[230:233], v[168:171], v[68:71]
	s_setprio 0
	v_lshl_add_u32 v2, v214, 1, s24
	ds_read_b128 v[218:221], v2 offset:4096
	ds_read_b128 v[222:225], v2 offset:5120
	ds_read_b128 v[226:229], v2 offset:6144
	ds_read_b128 v[230:233], v2 offset:7168
	s_setprio 1
	s_waitcnt lgkmcnt(0)
	v_mfma_f32_16x16x32_bf16 v[64:67], v[218:221], v[156:159], v[64:67]
	v_mfma_f32_16x16x32_bf16 v[60:63], v[218:221], v[160:163], v[60:63]
	v_mfma_f32_16x16x32_bf16 v[56:59], v[218:221], v[164:167], v[56:59]
	v_mfma_f32_16x16x32_bf16 v[52:55], v[218:221], v[168:171], v[52:55]
	v_mfma_f32_16x16x32_bf16 v[48:51], v[222:225], v[156:159], v[48:51]
	v_mfma_f32_16x16x32_bf16 v[44:47], v[222:225], v[160:163], v[44:47]
	v_mfma_f32_16x16x32_bf16 v[40:43], v[222:225], v[164:167], v[40:43]
	v_mfma_f32_16x16x32_bf16 v[36:39], v[222:225], v[168:171], v[36:39]
	v_mfma_f32_16x16x32_bf16 v[32:35], v[226:229], v[156:159], v[32:35]
	v_mfma_f32_16x16x32_bf16 v[28:31], v[226:229], v[160:163], v[28:31]
	v_mfma_f32_16x16x32_bf16 v[24:27], v[226:229], v[164:167], v[24:27]
	v_mfma_f32_16x16x32_bf16 v[20:23], v[226:229], v[168:171], v[20:23]
	v_mfma_f32_16x16x32_bf16 v[16:19], v[230:233], v[156:159], v[16:19]
	v_mfma_f32_16x16x32_bf16 v[12:15], v[230:233], v[160:163], v[12:15]
	v_mfma_f32_16x16x32_bf16 v[8:11], v[230:233], v[164:167], v[8:11]
	v_mfma_f32_16x16x32_bf16 v[4:7], v[230:233], v[168:171], v[4:7]
	s_setprio 0
	s_cmp_eq_u32 s2, 1
	s_cselect_b32 s2, 0x6000, 0
	v_lshl_add_u32 v2, v213, 1, s2
	s_waitcnt vmcnt(0)
	ds_write_b128 v2, v[132:135]
	ds_write_b128 v2, v[136:139] offset:4096
	ds_write_b128 v2, v[140:143] offset:8192
	ds_write_b128 v2, v[144:147] offset:12288
	ds_write_b128 v2, v[148:151] offset:16384
	ds_write_b128 v2, v[152:155] offset:20480
	v_lshl_add_u64 v[2:3], v[192:193], 0, s[20:21]
	global_load_dwordx4 v[132:135], v[2:3], off
	v_lshl_add_u64 v[2:3], v[190:191], 0, s[20:21]
	global_load_dwordx4 v[136:139], v[2:3], off
	v_lshl_add_u64 v[2:3], v[188:189], 0, s[20:21]
	global_load_dwordx4 v[140:143], v[2:3], off
	v_lshl_add_u64 v[2:3], v[186:187], 0, s[20:21]
	global_load_dwordx4 v[144:147], v[2:3], off
	v_lshl_add_u64 v[2:3], v[184:185], 0, s[20:21]
	v_lshl_add_u64 v[152:153], v[182:183], 0, s[20:21]
	global_load_dwordx4 v[148:151], v[2:3], off
	s_nop 0
	global_load_dwordx4 v[152:155], v[152:153], off
	s_add_u32 s20, s20, 64
	s_addc_u32 s21, s21, 0
	s_add_i32 s7, s7, 1
	s_cmpk_eq_i32 s20, 0x380
	s_waitcnt lgkmcnt(0)
	s_barrier
	s_cbranch_scc0 .Lp7a_fk
	s_branch .LBB0_1813

; __device__ __forceinline__ int vtid() { int t = threadIdx.x; asm volatile("" : "+v"(t)); return t; }
; template <int K, class FA, class FB, class Epi>
; __device__ __forceinline__ void gemm_tile(char* smem, int nvalid_rows, FA rowA, FB rowB, Epi epi) {
;   const int tid = vtid(), lane = tid & 63, wid = tid >> 6, wr = wid >> 1, wc = wid & 1, fr = lane & 15, fq = lane >> 4;
;   const int seg = tid & 3, r0 = tid >> 2;
;   int msub = (nvalid_rows - wr * 128 + 15) >> 4;
;   msub = msub < 0 ? 0 : (msub > 8 ? 8 : msub);
;   const u16* pa0 = rowA(r0) + seg * 8;
;   const u16* pa1 = rowA(r0 + 64) + seg * 8;
;   const u16* pa2 = rowA(r0 + 128) + seg * 8;
;   const u16* pa3 = rowA(r0 + 192) + seg * 8;
;   const u16* pb0 = rowB(r0) + seg * 8;
;   const u16* pb1 = rowB(r0 + 64) + seg * 8;
;   f32x4 acc[8][4];
; #pragma unroll
;   for (int m = 0; m < 8; ++m)
; #pragma unroll
;     for (int n = 0; n < 4; ++n) acc[m][n] = (f32x4){0.f, 0.f, 0.f, 0.f};
;   uint4 ra0, ra1, ra2, ra3, rb0, rb1;
;   ra0 = *(const uint4*)pa0; ra1 = *(const uint4*)pa1; ra2 = *(const uint4*)pa2; ra3 = *(const uint4*)pa3;
;   rb0 = *(const uint4*)pb0; rb1 = *(const uint4*)pb1;
;   constexpr int NK = K / 32;
;   const int wsw = (seg ^ ((r0 >> 2) & 3)) * 8;
;   const int wofsA = r0 * 32 + wsw, wofsB = 256 * 32 + r0 * 32 + wsw;
;   __syncthreads();
;   {
;     u16* B0 = (u16*)smem;
;     *(uint4*)&B0[wofsA] = ra0; *(uint4*)&B0[wofsA + 64 * 32] = ra1;
;     *(uint4*)&B0[wofsA + 128 * 32] = ra2; *(uint4*)&B0[wofsA + 192 * 32] = ra3;
;     *(uint4*)&B0[wofsB] = rb0; *(uint4*)&B0[wofsB + 64 * 32] = rb1;
;   }
;   ra0 = *(const uint4*)(pa0 + 32); ra1 = *(const uint4*)(pa1 + 32); ra2 = *(const uint4*)(pa2 + 32); ra3 = *(const uint4*)(pa3 + 32);
;   rb0 = *(const uint4*)(pb0 + 32); rb1 = *(const uint4*)(pb1 + 32);
;   __syncthreads();
;   const int rsw = (fq ^ ((fr >> 2) & 3)) * 8;
;   const int rdA = (wr * 128 + fr) * 32 + rsw, rdB = 256 * 32 + (wc * 64 + fr) * 32 + rsw;
; __device__ __forceinline__ void moe_down_tile(const Params& p, char* smem, int l, int e, int nt, int b, int mt, bool isctx, int ks) {
;     ...
;   auto rowA = [&](int r) {
;     if (isctx) { int s_ = r < 64 ? r : 0; return ACTC + ((size_t)(((s_ >> 5) * 16 + e) * 32 + (s_ & 31))) * 2048 + koff; }
;     return ACTL + (size_t)r * 2048;
;   };
;   auto rowB = [&](int r) { return W + (size_t)(nt * 128 + r) * 2048 + koff; };
.LBB0_1893:
	v_ashrrev_i32_e32 v5, 31, v4
	v_lshlrev_b32_e32 v0, 4, v10
	s_waitcnt vmcnt(0)
	v_lshlrev_b64 v[32:33], 12, v[4:5]
	v_and_b32_e32 v0, 48, v0
	v_lshl_add_u64 v[4:5], s[22:23], 0, v[32:33]
	v_ashrrev_i32_e32 v7, 31, v6
	s_lshl_b32 s6, s35, 7
	v_lshl_add_u64 v[34:35], v[4:5], 0, v[0:1]
	v_ashrrev_i32_e32 v3, 31, v2
	v_lshlrev_b64 v[40:41], 12, v[6:7]
	v_add_u32_e32 v4, s6, v11
	v_add_u32_e32 v6, s6, v12
	v_ashrrev_i32_e32 v9, 31, v8
	v_lshlrev_b64 v[36:37], 12, v[2:3]
	v_ashrrev_i32_e32 v5, 31, v4
	v_ashrrev_i32_e32 v7, 31, v6
	v_lshlrev_b64 v[28:29], 12, v[8:9]
	v_lshl_add_u64 v[2:3], s[20:21], 0, v[36:37]
	v_lshlrev_b64 v[42:43], 12, v[4:5]
	v_lshlrev_b64 v[44:45], 12, v[6:7]
	v_lshl_add_u64 v[8:9], s[24:25], 0, v[28:29]
	v_lshl_add_u64 v[38:39], v[2:3], 0, v[0:1]
	v_lshl_add_u64 v[2:3], s[14:15], 0, v[40:41]
	v_lshl_add_u64 v[4:5], s[16:17], 0, v[42:43]
	v_lshl_add_u64 v[6:7], s[16:17], 0, v[44:45]
	v_lshl_add_u64 v[30:31], v[8:9], 0, v[0:1]
	v_lshl_add_u64 v[46:47], v[2:3], 0, v[0:1]
	v_lshl_add_u64 v[48:49], v[4:5], 0, v[0:1]
	v_lshl_add_u64 v[50:51], v[6:7], 0, v[0:1]
	global_load_dwordx4 v[2:5], v[38:39], off
	global_load_dwordx4 v[6:9], v[34:35], off
	global_load_dwordx4 v[12:15], v[30:31], off
	global_load_dwordx4 v[16:19], v[46:47], off
	global_load_dwordx4 v[20:23], v[48:49], off
	global_load_dwordx4 v[24:27], v[50:51], off
	v_lshrrev_b32_e32 v179, 4, v10
	v_xor_b32_e32 v52, v179, v10
	v_lshlrev_b32_e32 v11, 5, v11
	v_lshlrev_b32_e32 v52, 3, v52
	v_and_or_b32 v213, v52, 24, v11
	v_lshlrev_b32_e32 v212, 1, v213
	s_waitcnt lgkmcnt(0)
	s_barrier
	v_and_b32_e32 v181, 0xffffff80, v10
	s_movk_i32 s0, 0xf1e0
	s_add_u32 s10, s10, 0x10e00080
	s_addc_u32 s11, s11, 0
	v_or_b32_e32 v40, v40, v0
	v_or_b32_e32 v28, v28, v0
	v_or_b32_e32 v32, v32, v0
	v_or_b32_e32 v36, v36, v0
	v_bfe_u32 v211, v10, 6, 1
	v_and_b32_e32 v180, 15, v10
	s_mov_b32 s2, 1
	v_lshlrev_b32_e32 v216, 12, v211
	v_lshlrev_b32_e32 v217, 6, v180
	s_waitcnt vmcnt(0)
	ds_write_b128 v212, v[2:5]
	ds_write_b128 v212, v[6:9] offset:4096
	ds_write_b128 v212, v[12:15] offset:8192
	ds_write_b128 v212, v[16:19] offset:12288
	ds_write_b128 v212, v[20:23] offset:16384
	ds_write_b128 v212, v[24:27] offset:20480
	global_load_dwordx4 v[132:135], v[38:39], off offset:64
	global_load_dwordx4 v[136:139], v[34:35], off offset:64
	global_load_dwordx4 v[140:143], v[30:31], off offset:64
	global_load_dwordx4 v[144:147], v[46:47], off offset:64
	global_load_dwordx4 v[148:151], v[48:49], off offset:64
	global_load_dwordx4 v[152:155], v[50:51], off offset:64
	v_lshrrev_b32_e32 v3, 2, v10
	v_xor_b32_e32 v3, v179, v3
	v_sub_u32_e32 v2, s28, v181
	v_lshlrev_b32_e32 v3, 3, v3
	v_ashrrev_i32_e32 v2, 4, v2
	v_and_b32_e32 v215, 24, v3
	v_lshlrev_b32_e32 v3, 5, v10
	v_and_or_b32 v214, v3, s0, v215
	v_cmp_lt_i32_e64 s[0:1], 0, v2
	v_cmp_lt_i32_e32 vcc, 4, v2
	v_lshl_add_u64 v[2:3], s[12:13], 0, v[44:45]
	v_lshl_add_u64 v[2:3], v[2:3], 0, v[0:1]
	v_lshl_add_u64 v[182:183], s[10:11], 0, v[2:3]
	v_lshl_add_u64 v[2:3], s[12:13], 0, v[42:43]
	v_lshl_add_u64 v[2:3], v[2:3], 0, v[0:1]
	v_lshl_add_u64 v[184:185], s[10:11], 0, v[2:3]
	v_lshl_add_u64 v[2:3], s[14:15], 0, v[40:41]
	s_mov_b64 s[10:11], 0x80
	v_lshl_add_u64 v[186:187], v[2:3], 0, s[10:11]
	v_lshl_add_u64 v[2:3], s[24:25], 0, v[28:29]
	v_lshl_add_u64 v[188:189], v[2:3], 0, s[10:11]
	v_lshl_add_u64 v[2:3], s[22:23], 0, v[32:33]
	v_lshl_add_u64 v[190:191], v[2:3], 0, s[10:11]
	v_lshl_add_u64 v[2:3], s[20:21], 0, v[36:37]
	v_lshl_add_u64 v[192:193], v[2:3], 0, s[10:11]
	v_mov_b32_e32 v2, v1
	v_mov_b32_e32 v3, v1
	v_mov_b32_e32 v0, v1
	v_mov_b64_e32 v[6:7], v[2:3]
	v_mov_b64_e32 v[10:11], v[2:3]
	v_mov_b64_e32 v[14:15], v[2:3]
	v_mov_b64_e32 v[18:19], v[2:3]
	v_mov_b64_e32 v[22:23], v[2:3]
	v_mov_b64_e32 v[26:27], v[2:3]
	v_mov_b64_e32 v[30:31], v[2:3]
	v_mov_b64_e32 v[34:35], v[2:3]
	v_mov_b64_e32 v[38:39], v[2:3]
	v_mov_b64_e32 v[42:43], v[2:3]
	v_mov_b64_e32 v[46:47], v[2:3]
	v_mov_b64_e32 v[50:51], v[2:3]
	v_mov_b64_e32 v[54:55], v[2:3]
	v_mov_b64_e32 v[58:59], v[2:3]
	v_mov_b64_e32 v[62:63], v[2:3]
	v_mov_b64_e32 v[66:67], v[2:3]
	v_mov_b64_e32 v[70:71], v[2:3]
	v_mov_b64_e32 v[74:75], v[2:3]
	v_mov_b64_e32 v[78:79], v[2:3]
	v_mov_b64_e32 v[82:83], v[2:3]
	v_mov_b64_e32 v[86:87], v[2:3]
	v_mov_b64_e32 v[90:91], v[2:3]
	v_mov_b64_e32 v[94:95], v[2:3]
	v_mov_b64_e32 v[98:99], v[2:3]
	v_mov_b64_e32 v[102:103], v[2:3]
	v_mov_b64_e32 v[106:107], v[2:3]
	v_mov_b64_e32 v[110:111], v[2:3]
	v_mov_b64_e32 v[114:115], v[2:3]
	v_mov_b64_e32 v[118:119], v[2:3]
	v_mov_b64_e32 v[122:123], v[2:3]
	v_mov_b64_e32 v[126:127], v[2:3]
	v_mov_b64_e32 v[130:131], v[2:3]
	s_mov_b64 s[10:11], 0
	v_mov_b64_e32 v[4:5], v[0:1]
	v_mov_b64_e32 v[8:9], v[0:1]
	v_mov_b64_e32 v[12:13], v[0:1]
	v_mov_b64_e32 v[16:17], v[0:1]
	v_mov_b64_e32 v[20:21], v[0:1]
	v_mov_b64_e32 v[24:25], v[0:1]
	v_mov_b64_e32 v[28:29], v[0:1]
	v_mov_b64_e32 v[32:33], v[0:1]
	v_mov_b64_e32 v[36:37], v[0:1]
	v_mov_b64_e32 v[40:41], v[0:1]
	v_mov_b64_e32 v[44:45], v[0:1]
	v_mov_b64_e32 v[48:49], v[0:1]
	v_mov_b64_e32 v[52:53], v[0:1]
	v_mov_b64_e32 v[56:57], v[0:1]
	v_mov_b64_e32 v[60:61], v[0:1]
	v_mov_b64_e32 v[64:65], v[0:1]
	v_mov_b64_e32 v[68:69], v[0:1]
	v_mov_b64_e32 v[72:73], v[0:1]
	v_mov_b64_e32 v[76:77], v[0:1]
	v_mov_b64_e32 v[80:81], v[0:1]
	v_mov_b64_e32 v[84:85], v[0:1]
	v_mov_b64_e32 v[88:89], v[0:1]
	v_mov_b64_e32 v[92:93], v[0:1]
	v_mov_b64_e32 v[96:97], v[0:1]
	v_mov_b64_e32 v[100:101], v[0:1]
	v_mov_b64_e32 v[104:105], v[0:1]
	v_mov_b64_e32 v[108:109], v[0:1]
	v_mov_b64_e32 v[112:113], v[0:1]
	v_mov_b64_e32 v[116:117], v[0:1]
	v_mov_b64_e32 v[120:121], v[0:1]
	v_mov_b64_e32 v[124:125], v[0:1]
	v_mov_b64_e32 v[128:129], v[0:1]
	s_waitcnt lgkmcnt(0)
	s_barrier
	s_and_b64 s[12:13], s[0:1], vcc
	s_cmp_eq_u64 s[12:13], exec
	s_cbranch_scc1 .Lp7b_fk
	s_branch .LBB0_1895
; template <int K, class FA, class FB, class Epi>
; __device__ __forceinline__ void gemm_tile(char* smem, int nvalid_rows, FA rowA, FB rowB, Epi epi) {
;     ...
;   for (int kt = 0; kt < NK; ++kt) {
;     const u16* Bc = (const u16*)(smem + (kt & 1) * 24576);
;     bf16x8 Bt[4];
; #pragma unroll
;     for (int n = 0; n < 4; ++n) Bt[n] = *(const bf16x8*)&Bc[rdB + n * 16 * 32];
;     if (msub > 0) {
;       bf16x8 At[4];
; #pragma unroll
;       for (int m = 0; m < 4; ++m) At[m] = *(const bf16x8*)&Bc[rdA + m * 16 * 32];
;       __builtin_amdgcn_s_setprio(1);
; #pragma unroll
;       for (int m = 0; m < 4; ++m)
; #pragma unroll
;         for (int n = 0; n < 4; ++n) acc[m][n] = __builtin_amdgcn_mfma_f32_16x16x32_bf16(At[m], Bt[n], acc[m][n], 0, 0, 0);
;       __builtin_amdgcn_s_setprio(0);
;     }
;     if (msub > 4) {
;       bf16x8 At[4];
; #pragma unroll
;       for (int m = 0; m < 4; ++m) At[m] = *(const bf16x8*)&Bc[rdA + (m + 4) * 16 * 32];
;       __builtin_amdgcn_s_setprio(1);
; #pragma unroll
;       for (int m = 0; m < 4; ++m)
; #pragma unroll
;         for (int n = 0; n < 4; ++n) acc[m + 4][n] = __builtin_amdgcn_mfma_f32_16x16x32_bf16(At[m], Bt[n], acc[m + 4][n], 0, 0, 0);
;       __builtin_amdgcn_s_setprio(0);
;     }
;     if (kt + 1 < NK) {
;       u16* Bn = (u16*)(smem + ((kt + 1) & 1) * 24576);
;       *(uint4*)&Bn[wofsA] = ra0; *(uint4*)&Bn[wofsA + 64 * 32] = ra1;
;       *(uint4*)&Bn[wofsA + 128 * 32] = ra2; *(uint4*)&Bn[wofsA + 192 * 32] = ra3;
;       *(uint4*)&Bn[wofsB] = rb0; *(uint4*)&Bn[wofsB + 64 * 32] = rb1;
;     }
;     if (kt + 2 < NK) {
;       const int ko = (kt + 2) * 32;
;       ra0 = *(const uint4*)(pa0 + ko); ra1 = *(const uint4*)(pa1 + ko); ra2 = *(const uint4*)(pa2 + ko); ra3 = *(const uint4*)(pa3 + ko);
;       rb0 = *(const uint4*)(pb0 + ko); rb1 = *(const uint4*)(pb1 + ko);
;     }
;     __syncthreads();
;   }
.Lp7b_fk:
	s_and_b32 s7, 1, s2
	s_cselect_b32 s14, 0, 0x6000
	v_or_b32_e32 v2, s14, v216
	v_lshlrev_b32_e32 v0, 1, v215
	v_add3_u32 v2, v2, v217, v0
	ds_read_b128 v[156:159], v2 offset:16384
	ds_read_b128 v[160:163], v2 offset:17408
	ds_read_b128 v[164:167], v2 offset:18432
	ds_read_b128 v[168:171], v2 offset:19456
	v_lshl_add_u32 v2, v214, 1, s14
	ds_read_b128 v[218:221], v2
	ds_read_b128 v[222:225], v2 offset:1024
	ds_read_b128 v[226:229], v2 offset:2048
	ds_read_b128 v[230:233], v2 offset:3072
	s_setprio 1
	s_waitcnt lgkmcnt(0)
	v_mfma_f32_16x16x32_bf16 v[128:131], v[218:221], v[156:159], v[128:131]
	v_mfma_f32_16x16x32_bf16 v[124:127], v[218:221], v[160:163], v[124:127]
	v_mfma_f32_16x16x32_bf16 v[120:123], v[218:221], v[164:167], v[120:123]
	v_mfma_f32_16x16x32_bf16 v[116:119], v[218:221], v[168:171], v[116:119]
	v_mfma_f32_16x16x32_bf16 v[112:115], v[222:225], v[156:159], v[112:115]
	v_mfma_f32_16x16x32_bf16 v[108:111], v[222:225], v[160:163], v[108:111]
	v_mfma_f32_16x16x32_bf16 v[104:107], v[222:225], v[164:167], v[104:107]
	v_mfma_f32_16x16x32_bf16 v[100:103], v[222:225], v[168:171], v[100:103]
	v_mfma_f32_16x16x32_bf16 v[96:99], v[226:229], v[156:159], v[96:99]
	v_mfma_f32_16x16x32_bf16 v[92:95], v[226:229], v[160:163], v[92:95]
	v_mfma_f32_16x16x32_bf16 v[88:91], v[226:229], v[164:167], v[88:91]
	v_mfma_f32_16x16x32_bf16 v[84:87], v[226:229], v[168:171], v[84:87]
	v_mfma_f32_16x16x32_bf16 v[80:83], v[230:233], v[156:159], v[80:83]
	v_mfma_f32_16x16x32_bf16 v[76:79], v[230:233], v[160:163], v[76:79]
	v_mfma_f32_16x16x32_bf16 v[72:75], v[230:233], v[164:167], v[72:75]
	v_mfma_f32_16x16x32_bf16 v[68:71], v[230:233], v[168:171], v[68:71]
	s_setprio 0
	v_lshl_add_u32 v2, v214, 1, s14
	ds_read_b128 v[218:221], v2 offset:4096
	ds_read_b128 v[222:225], v2 offset:5120
	ds_read_b128 v[226:229], v2 offset:6144
	ds_read_b128 v[230:233], v2 offset:7168
	s_setprio 1
	s_waitcnt lgkmcnt(0)
	v_mfma_f32_16x16x32_bf16 v[64:67], v[218:221], v[156:159], v[64:67]
	v_mfma_f32_16x16x32_bf16 v[60:63], v[218:221], v[160:163], v[60:63]
	v_mfma_f32_16x16x32_bf16 v[56:59], v[218:221], v[164:167], v[56:59]
	v_mfma_f32_16x16x32_bf16 v[52:55], v[218:221], v[168:171], v[52:55]
	v_mfma_f32_16x16x32_bf16 v[48:51], v[222:225], v[156:159], v[48:51]
	v_mfma_f32_16x16x32_bf16 v[44:47], v[222:225], v[160:163], v[44:47]
	v_mfma_f32_16x16x32_bf16 v[40:43], v[222:225], v[164:167], v[40:43]
	v_mfma_f32_16x16x32_bf16 v[36:39], v[222:225], v[168:171], v[36:39]
	v_mfma_f32_16x16x32_bf16 v[32:35], v[226:229], v[156:159], v[32:35]
	v_mfma_f32_16x16x32_bf16 v[28:31], v[226:229], v[160:163], v[28:31]
	v_mfma_f32_16x16x32_bf16 v[24:27], v[226:229], v[164:167], v[24:27]
	v_mfma_f32_16x16x32_bf16 v[20:23], v[226:229], v[168:171], v[20:23]
	v_mfma_f32_16x16x32_bf16 v[16:19], v[230:233], v[156:159], v[16:19]
	v_mfma_f32_16x16x32_bf16 v[12:15], v[230:233], v[160:163], v[12:15]
	v_mfma_f32_16x16x32_bf16 v[8:11], v[230:233], v[164:167], v[8:11]
	v_mfma_f32_16x16x32_bf16 v[4:7], v[230:233], v[168:171], v[4:7]
	s_setprio 0
	s_cmp_eq_u32 s7, 1
	s_cselect_b32 s7, 0x6000, 0
	v_lshl_add_u32 v2, v213, 1, s7
	s_waitcnt vmcnt(0)
	ds_write_b128 v2, v[132:135]
	ds_write_b128 v2, v[136:139] offset:4096
	ds_write_b128 v2, v[140:143] offset:8192
	ds_write_b128 v2, v[144:147] offset:12288
	ds_write_b128 v2, v[148:151] offset:16384
	ds_write_b128 v2, v[152:155] offset:20480
	v_lshl_add_u64 v[2:3], v[192:193], 0, s[10:11]
	global_load_dwordx4 v[132:135], v[2:3], off
	v_lshl_add_u64 v[2:3], v[190:191], 0, s[10:11]
	global_load_dwordx4 v[136:139], v[2:3], off
	v_lshl_add_u64 v[2:3], v[188:189], 0, s[10:11]
	global_load_dwordx4 v[140:143], v[2:3], off
	v_lshl_add_u64 v[2:3], v[186:187], 0, s[10:11]
	global_load_dwordx4 v[144:147], v[2:3], off
	v_lshl_add_u64 v[2:3], v[184:185], 0, s[10:11]
	v_lshl_add_u64 v[152:153], v[182:183], 0, s[10:11]
	global_load_dwordx4 v[148:151], v[2:3], off
	s_nop 0
	global_load_dwordx4 v[152:155], v[152:153], off
	s_add_u32 s10, s10, 64
	s_addc_u32 s11, s11, 0
	s_add_i32 s2, s2, 1
	s_cmpk_eq_i32 s10, 0xf80
	s_waitcnt lgkmcnt(0)
	s_barrier
	s_cbranch_scc0 .Lp7b_fk
	s_branch .LBB0_1899
